# speedup vs baseline: 1.0087x; 1.0087x over previous
; #define MFMA(a, b, c) __builtin_amdgcn_mfma_f32_32x32x16_bf16((a), (b), (c), 0, 0, 0)
; DI unsigned pack2(float a, float b) { v2f f = {a, b}; return __builtin_bit_cast(unsigned, __builtin_convertvector(f, v2bf)); }
; DI float fexp2(float x) { return __builtin_amdgcn_exp2f(x); }
; template <int DV, int STEP>
; DI void pv_step(f32x16 (&ot)[DV / 32], const bf16x8 (&pk)[2][2], s16x4 (&fa)[DV / 32][2], s16x4 (&fb)[DV / 32][2], const unsigned (&a)[DV / 32]) {
;   constexpr int VP = 2 * DV, NDC = DV / 32;
;   tr_wait(fa);
;   if (STEP < 3) TrIssue<NDC, (((STEP + 1) >> 1) * 32 + ((STEP + 1) & 1) * 16) * VP, (((STEP + 1) >> 1) * 32 + ((STEP + 1) & 1) * 16 + 8) * VP>::run(fb, a);
; #pragma unroll
;   for (int dc = 0; dc < NDC; ++dc) {
;     const bf16x8 vf = __builtin_shufflevector(fa[dc][0], fa[dc][1], 0, 1, 2, 3, 4, 5, 6, 7);
;     ot[dc] = MFMA(vf, pk[STEP >> 1][STEP & 1], ot[dc]);
;   }
; }
; template <int DV, bool SEL, bool TERM> ...
;     ...
;       bf16x8 pk[2][2];
; #pragma unroll
;       for (int kb = 0; kb < 2; ++kb)
; #pragma unroll
;         for (int s2 = 0; s2 < 2; ++s2) {
;           unsigned w[4];
; #pragma unroll
;           for (int j = 0; j < 4; ++j) {
;             w[j] = pack2(fexp2(st[kb][8 * s2 + 2 * j]), fexp2(st[kb][8 * s2 + 2 * j + 1]));
;             l = dot2ones(w[j], l);
;           }
;           u32x4 v = {w[0], w[1], w[2], w[3]};
;           pk[kb][s2] = __builtin_bit_cast(bf16x8, v);
;         }
;       pv_tile<DV>(ot, pk, sb, lane);
;       if (TERM) {
;         const float bound = qb - slope2 * (float)(tqp - kp_mul * (k0 - 1)) - mref;
;         done = __all(bound < -150.f) ? 1u : 0u;
.LBB0_835:
	v_exp_f32_e32 v0, v2
	v_exp_f32_e32 v18, v3
	v_exp_f32_e32 v19, v4
	v_exp_f32_e32 v20, v6
	v_exp_f32_e32 v21, v7
	v_cvt_pk_bf16_f32 v18, v0, v18
	v_exp_f32_e32 v0, v5
	v_exp_f32_e32 v22, v10
	v_cvt_pk_bf16_f32 v20, v20, v21
	v_exp_f32_e32 v21, v9
	v_cvt_pk_bf16_f32 v19, v19, v0
	v_exp_f32_e32 v0, v8
	v_exp_f32_e32 v23, v11
	s_add_i32 s1, s16, s1
	s_addk_i32 s1, 0x2000
	v_add_u32_e32 v28, s1, v119
	v_cvt_pk_bf16_f32 v21, v0, v21
	v_cvt_pk_bf16_f32 v22, v22, v23
	v_exp_f32_e32 v0, v12
	v_exp_f32_e32 v23, v13
	v_exp_f32_e32 v24, v14
	v_exp_f32_e32 v25, v15
	v_add_u32_e32 v137, v28, v120
	v_add_u32_e32 v138, v28, v121
	ds_read_b64_tr_b16 v[28:29], v137 offset:0
	ds_read_b64_tr_b16 v[30:31], v137 offset:0x400
	ds_read_b64_tr_b16 v[132:133], v138 offset:0
	ds_read_b64_tr_b16 v[134:135], v138 offset:0x400
	v_cvt_pk_bf16_f32 v23, v0, v23
	s_waitcnt lgkmcnt(0)
	v_cvt_pk_bf16_f32 v24, v24, v25
	v_mfma_f32_32x32x16_bf16 v[32:47], v[28:31], v[18:21], v[32:47]
	v_exp_f32_e32 v0, v16
	v_exp_f32_e32 v25, v17
	v_exp_f32_e32 v26, v64
	v_exp_f32_e32 v27, v65
	v_dot2c_f32_bf16_e32 v115, 0x3f803f80, v18
	v_dot2c_f32_bf16_e32 v115, 0x3f803f80, v19
	v_dot2c_f32_bf16_e32 v115, 0x3f803f80, v20
	v_mfma_f32_32x32x16_bf16 v[48:63], v[132:135], v[18:21], v[48:63]
	v_dot2c_f32_bf16_e32 v115, 0x3f803f80, v21
	v_cvt_pk_bf16_f32 v25, v0, v25
	v_cvt_pk_bf16_f32 v26, v26, v27
	v_exp_f32_e32 v0, v66
	v_exp_f32_e32 v27, v67
	ds_read_b64_tr_b16 v[132:133], v137 offset:0x800
	ds_read_b64_tr_b16 v[134:135], v137 offset:0xc00
	ds_read_b64_tr_b16 v[18:19], v138 offset:0x800
	ds_read_b64_tr_b16 v[20:21], v138 offset:0xc00
	v_exp_f32_e32 v136, v68
	v_exp_f32_e32 v28, v69
	s_waitcnt lgkmcnt(2)
	v_mfma_f32_32x32x16_bf16 v[32:47], v[132:135], v[22:25], v[32:47]
	v_cvt_pk_bf16_f32 v27, v0, v27
	v_exp_f32_e32 v0, v70
	v_exp_f32_e32 v29, v71
	v_dot2c_f32_bf16_e32 v115, 0x3f803f80, v22
	v_dot2c_f32_bf16_e32 v115, 0x3f803f80, v23
	v_dot2c_f32_bf16_e32 v115, 0x3f803f80, v24
	v_dot2c_f32_bf16_e32 v115, 0x3f803f80, v25
	s_waitcnt lgkmcnt(0)
	v_mfma_f32_32x32x16_bf16 v[48:63], v[18:21], v[22:25], v[48:63]
	v_cvt_pk_bf16_f32 v28, v136, v28
	v_cvt_pk_bf16_f32 v29, v0, v29
	ds_read_b64_tr_b16 v[22:23], v137 offset:0x1000
	ds_read_b64_tr_b16 v[24:25], v137 offset:0x1400
	ds_read_b64_tr_b16 v[18:19], v138 offset:0x1000
	ds_read_b64_tr_b16 v[20:21], v138 offset:0x1400
	v_exp_f32_e32 v0, v72
	v_exp_f32_e32 v30, v73
	v_exp_f32_e32 v31, v74
	s_waitcnt lgkmcnt(2)
	v_mfma_f32_32x32x16_bf16 v[32:47], v[22:25], v[26:29], v[32:47]
	v_exp_f32_e32 v132, v75
	v_exp_f32_e32 v133, v76
	v_exp_f32_e32 v24, v77
	v_exp_f32_e32 v25, v78
	v_exp_f32_e32 v134, v79
	v_cvt_pk_bf16_f32 v22, v0, v30
	v_subrev_u32_e32 v0, s0, v122
	s_waitcnt lgkmcnt(0)
	v_mfma_f32_32x32x16_bf16 v[48:63], v[18:21], v[26:29], v[48:63]
	v_cvt_f32_i32_e32 v0, v0
	v_cvt_pk_bf16_f32 v23, v31, v132
	v_cvt_pk_bf16_f32 v24, v133, v24
	v_cvt_pk_bf16_f32 v25, v25, v134
	ds_read_b64_tr_b16 v[132:133], v137 offset:0x1800
	ds_read_b64_tr_b16 v[134:135], v137 offset:0x1c00
	ds_read_b64_tr_b16 v[18:19], v138 offset:0x1800
	ds_read_b64_tr_b16 v[20:21], v138 offset:0x1c00
	v_dot2c_f32_bf16_e32 v115, 0x3f803f80, v26
	v_dot2c_f32_bf16_e32 v115, 0x3f803f80, v27
	s_waitcnt lgkmcnt(2)
	v_mfma_f32_32x32x16_bf16 v[32:47], v[132:135], v[22:25], v[32:47]
	v_dot2c_f32_bf16_e32 v115, 0x3f803f80, v28
	v_fma_f32 v0, -v182, v0, v116
	v_dot2c_f32_bf16_e32 v115, 0x3f803f80, v29
	v_sub_f32_e32 v0, v0, v108
	v_dot2c_f32_bf16_e32 v115, 0x3f803f80, v22
	v_cmp_gt_f32_e32 vcc, s3, v0
	v_dot2c_f32_bf16_e32 v115, 0x3f803f80, v23
	s_waitcnt lgkmcnt(0)
	v_mfma_f32_32x32x16_bf16 v[48:63], v[18:21], v[22:25], v[48:63]
	s_cmp_eq_u64 vcc, exec
	v_dot2c_f32_bf16_e32 v115, 0x3f803f80, v24
	s_cselect_b64 s[0:1], -1, 0
	v_dot2c_f32_bf16_e32 v115, 0x3f803f80, v25
	v_cndmask_b32_e64 v132, 0, 1, s[0:1]

; #define MFMA(a, b, c) __builtin_amdgcn_mfma_f32_32x32x16_bf16((a), (b), (c), 0, 0, 0)
; DI unsigned pack2(float a, float b) { v2f f = {a, b}; return __builtin_bit_cast(unsigned, __builtin_convertvector(f, v2bf)); }
; DI float fexp2(float x) { return __builtin_amdgcn_exp2f(x); }
; template <int DV, int STEP>
; DI void pv_step(f32x16 (&ot)[DV / 32], const bf16x8 (&pk)[2][2], s16x4 (&fa)[DV / 32][2], s16x4 (&fb)[DV / 32][2], const unsigned (&a)[DV / 32]) {
;   constexpr int VP = 2 * DV, NDC = DV / 32;
;   tr_wait(fa);
;   if (STEP < 3) TrIssue<NDC, (((STEP + 1) >> 1) * 32 + ((STEP + 1) & 1) * 16) * VP, (((STEP + 1) >> 1) * 32 + ((STEP + 1) & 1) * 16 + 8) * VP>::run(fb, a);
; #pragma unroll
;   for (int dc = 0; dc < NDC; ++dc) {
;     const bf16x8 vf = __builtin_shufflevector(fa[dc][0], fa[dc][1], 0, 1, 2, 3, 4, 5, 6, 7);
;     ot[dc] = MFMA(vf, pk[STEP >> 1][STEP & 1], ot[dc]);
;   }
; }
; template <int DV, bool SEL, bool TERM> ...
;     ...
;       bf16x8 pk[2][2];
; #pragma unroll
;       for (int kb = 0; kb < 2; ++kb)
; #pragma unroll
;         for (int s2 = 0; s2 < 2; ++s2) {
;           unsigned w[4];
; #pragma unroll
;           for (int j = 0; j < 4; ++j) {
;             w[j] = pack2(fexp2(st[kb][8 * s2 + 2 * j]), fexp2(st[kb][8 * s2 + 2 * j + 1]));
;             l = dot2ones(w[j], l);
;           }
;           u32x4 v = {w[0], w[1], w[2], w[3]};
;           pk[kb][s2] = __builtin_bit_cast(bf16x8, v);
;         }
;       pv_tile<DV>(ot, pk, sb, lane);
;       if (TERM) {
;         const float bound = qb - slope2 * (float)(tqp - kp_mul * (k0 - 1)) - mref;
;         done = __all(bound < -150.f) ? 1u : 0u;
.LBB0_953:
	v_exp_f32_e32 v0, v96
	v_exp_f32_e32 v2, v97
	v_exp_f32_e32 v3, v98
	v_exp_f32_e32 v4, v99
	v_exp_f32_e32 v5, v101
	v_cvt_pk_bf16_f32 v2, v0, v2
	v_exp_f32_e32 v0, v100
	v_cvt_pk_bf16_f32 v3, v3, v4
	v_exp_f32_e32 v6, v104
	v_exp_f32_e32 v7, v105
	v_cvt_pk_bf16_f32 v4, v0, v5
	v_exp_f32_e32 v0, v102
	v_exp_f32_e32 v5, v103
	s_addk_i32 s20, 0x2000
	v_add_u32_e32 v13, s20, v248
	v_cvt_pk_bf16_f32 v6, v6, v7
	v_cvt_pk_bf16_f32 v5, v0, v5
	v_exp_f32_e32 v0, v106
	v_exp_f32_e32 v7, v107
	v_exp_f32_e32 v8, v108
	v_exp_f32_e32 v9, v109
	v_add_u32_e32 v22, v13, v249
	v_add_u32_e32 v23, v13, v250
	ds_read_b64_tr_b16 v[18:19], v22 offset:0
	ds_read_b64_tr_b16 v[20:21], v22 offset:0x400
	ds_read_b64_tr_b16 v[14:15], v23 offset:0
	ds_read_b64_tr_b16 v[16:17], v23 offset:0x400
	v_cvt_pk_bf16_f32 v7, v0, v7
	s_waitcnt lgkmcnt(0)
	v_cvt_pk_bf16_f32 v8, v8, v9
	v_mfma_f32_32x32x16_bf16 v[64:79], v[18:21], v[2:5], v[64:79]
	v_exp_f32_e32 v0, v110
	v_exp_f32_e32 v9, v111
	v_exp_f32_e32 v10, v112
	v_exp_f32_e32 v11, v113
	v_dot2c_f32_bf16_e32 v233, 0x3f803f80, v2
	v_dot2c_f32_bf16_e32 v233, 0x3f803f80, v3
	v_dot2c_f32_bf16_e32 v233, 0x3f803f80, v4
	v_mfma_f32_32x32x16_bf16 v[80:95], v[14:17], v[2:5], v[80:95]
	v_dot2c_f32_bf16_e32 v233, 0x3f803f80, v5
	v_cvt_pk_bf16_f32 v9, v0, v9
	v_cvt_pk_bf16_f32 v10, v10, v11
	v_exp_f32_e32 v0, v114
	v_exp_f32_e32 v11, v115
	v_exp_f32_e32 v12, v116
	v_exp_f32_e32 v13, v117
	ds_read_b64_tr_b16 v[14:15], v22 offset:0x800
	ds_read_b64_tr_b16 v[16:17], v22 offset:0xc00
	ds_read_b64_tr_b16 v[2:3], v23 offset:0x800
	ds_read_b64_tr_b16 v[4:5], v23 offset:0xc00
	v_cvt_pk_bf16_f32 v11, v0, v11
	v_cvt_pk_bf16_f32 v12, v12, v13
	s_waitcnt lgkmcnt(2)
	v_mfma_f32_32x32x16_bf16 v[64:79], v[14:17], v[6:9], v[64:79]
	v_exp_f32_e32 v0, v118
	v_exp_f32_e32 v13, v119
	v_dot2c_f32_bf16_e32 v233, 0x3f803f80, v6
	v_dot2c_f32_bf16_e32 v233, 0x3f803f80, v7
	v_dot2c_f32_bf16_e32 v233, 0x3f803f80, v8
	v_dot2c_f32_bf16_e32 v233, 0x3f803f80, v9
	v_cvt_pk_bf16_f32 v13, v0, v13
	s_waitcnt lgkmcnt(0)
	v_mfma_f32_32x32x16_bf16 v[80:95], v[2:5], v[6:9], v[80:95]
	ds_read_b64_tr_b16 v[6:7], v22 offset:0x1000
	ds_read_b64_tr_b16 v[8:9], v22 offset:0x1400
	ds_read_b64_tr_b16 v[2:3], v23 offset:0x1000
	ds_read_b64_tr_b16 v[4:5], v23 offset:0x1400
	v_exp_f32_e32 v0, v120
	v_exp_f32_e32 v14, v121
	v_exp_f32_e32 v15, v122
	v_exp_f32_e32 v16, v123
	v_exp_f32_e32 v17, v124
	s_waitcnt lgkmcnt(2)
	v_mfma_f32_32x32x16_bf16 v[64:79], v[6:9], v[10:13], v[64:79]
	v_exp_f32_e32 v8, v125
	v_exp_f32_e32 v9, v126
	v_exp_f32_e32 v18, v127
	v_cvt_pk_bf16_f32 v6, v0, v14
	v_subrev_u32_e32 v0, s19, v232
	v_cvt_f32_i32_e32 v0, v0
	v_cvt_pk_bf16_f32 v7, v15, v16
	s_waitcnt lgkmcnt(0)
	v_mfma_f32_32x32x16_bf16 v[80:95], v[2:5], v[10:13], v[80:95]
	v_cvt_pk_bf16_f32 v8, v17, v8
	v_cvt_pk_bf16_f32 v9, v9, v18
	ds_read_b64_tr_b16 v[14:15], v22 offset:0x1800
	ds_read_b64_tr_b16 v[16:17], v22 offset:0x1c00
	ds_read_b64_tr_b16 v[2:3], v23 offset:0x1800
	ds_read_b64_tr_b16 v[4:5], v23 offset:0x1c00
	v_dot2c_f32_bf16_e32 v233, 0x3f803f80, v10
	v_dot2c_f32_bf16_e32 v233, 0x3f803f80, v11
	v_dot2c_f32_bf16_e32 v233, 0x3f803f80, v12
	s_waitcnt lgkmcnt(2)
	v_mfma_f32_32x32x16_bf16 v[64:79], v[14:17], v[6:9], v[64:79]
	v_fma_f32 v0, -v182, v0, v246
	v_dot2c_f32_bf16_e32 v233, 0x3f803f80, v13
	v_sub_f32_e32 v0, v0, v252
	v_dot2c_f32_bf16_e32 v233, 0x3f803f80, v6
	v_cmp_gt_f32_e32 vcc, s3, v0
	v_dot2c_f32_bf16_e32 v233, 0x3f803f80, v7
	s_cmp_eq_u64 vcc, exec
	s_waitcnt lgkmcnt(0)
	v_mfma_f32_32x32x16_bf16 v[80:95], v[2:5], v[6:9], v[80:95]
	v_dot2c_f32_bf16_e32 v233, 0x3f803f80, v8
	s_cselect_b64 s[0:1], -1, 0
	v_mov_b64_e32 v[158:159], v[126:127]
	v_dot2c_f32_bf16_e32 v233, 0x3f803f80, v9
	v_cndmask_b32_e64 v253, 0, 1, s[0:1]
	v_mov_b64_e32 v[156:157], v[124:125]
	v_mov_b64_e32 v[154:155], v[122:123]
	v_mov_b64_e32 v[152:153], v[120:121]
	v_mov_b64_e32 v[150:151], v[118:119]
	v_mov_b64_e32 v[148:149], v[116:117]
	v_mov_b64_e32 v[146:147], v[114:115]
	v_mov_b64_e32 v[144:145], v[112:113]
	v_mov_b64_e32 v[142:143], v[110:111]
	v_mov_b64_e32 v[140:141], v[108:109]
	v_mov_b64_e32 v[138:139], v[106:107]
	v_mov_b64_e32 v[136:137], v[104:105]
	v_mov_b64_e32 v[134:135], v[102:103]
	v_mov_b64_e32 v[132:133], v[100:101]
	v_mov_b64_e32 v[130:131], v[98:99]
	v_mov_b64_e32 v[128:129], v[96:97]

; #define MFMA(a, b, c) __builtin_amdgcn_mfma_f32_32x32x16_bf16((a), (b), (c), 0, 0, 0)
; DI unsigned pack2(float a, float b) { v2f f = {a, b}; return __builtin_bit_cast(unsigned, __builtin_convertvector(f, v2bf)); }
; DI float fexp2(float x) { return __builtin_amdgcn_exp2f(x); }
; template <int DV, int STEP>
; DI void pv_step(f32x16 (&ot)[DV / 32], const bf16x8 (&pk)[2][2], s16x4 (&fa)[DV / 32][2], s16x4 (&fb)[DV / 32][2], const unsigned (&a)[DV / 32]) {
;   constexpr int VP = 2 * DV, NDC = DV / 32;
;   tr_wait(fa);
;   if (STEP < 3) TrIssue<NDC, (((STEP + 1) >> 1) * 32 + ((STEP + 1) & 1) * 16) * VP, (((STEP + 1) >> 1) * 32 + ((STEP + 1) & 1) * 16 + 8) * VP>::run(fb, a);
; #pragma unroll
;   for (int dc = 0; dc < NDC; ++dc) {
;     const bf16x8 vf = __builtin_shufflevector(fa[dc][0], fa[dc][1], 0, 1, 2, 3, 4, 5, 6, 7);
;     ot[dc] = MFMA(vf, pk[STEP >> 1][STEP & 1], ot[dc]);
;   }
; }
; template <int DV, bool SEL, bool TERM> ...
;     ...
;       bf16x8 pk[2][2];
; #pragma unroll
;       for (int kb = 0; kb < 2; ++kb)
; #pragma unroll
;         for (int s2 = 0; s2 < 2; ++s2) {
;           unsigned w[4];
; #pragma unroll
;           for (int j = 0; j < 4; ++j) {
;             w[j] = pack2(fexp2(st[kb][8 * s2 + 2 * j]), fexp2(st[kb][8 * s2 + 2 * j + 1]));
;             l = dot2ones(w[j], l);
;           }
;           u32x4 v = {w[0], w[1], w[2], w[3]};
;           pk[kb][s2] = __builtin_bit_cast(bf16x8, v);
;         }
;       pv_tile<DV>(ot, pk, sb, lane);
;       if (TERM) {
;         const float bound = qb - slope2 * (float)(tqp - kp_mul * (k0 - 1)) - mref;
;         done = __all(bound < -150.f) ? 1u : 0u;
.LBB0_983:
	v_exp_f32_e32 v0, v2
	v_exp_f32_e32 v18, v3
	v_exp_f32_e32 v19, v4
	v_exp_f32_e32 v20, v6
	v_exp_f32_e32 v21, v7
	v_cvt_pk_bf16_f32 v18, v0, v18
	v_exp_f32_e32 v0, v5
	v_exp_f32_e32 v22, v10
	v_cvt_pk_bf16_f32 v20, v20, v21
	v_exp_f32_e32 v21, v9
	v_cvt_pk_bf16_f32 v19, v19, v0
	v_exp_f32_e32 v0, v8
	v_exp_f32_e32 v23, v11
	s_add_i32 s1, s18, s1
	s_addk_i32 s1, 0x2000
	v_add_u32_e32 v28, s1, v199
	v_cvt_pk_bf16_f32 v21, v0, v21
	v_cvt_pk_bf16_f32 v22, v22, v23
	v_exp_f32_e32 v0, v12
	v_exp_f32_e32 v23, v13
	v_exp_f32_e32 v24, v14
	v_exp_f32_e32 v25, v15
	v_add_u32_e32 v244, v28, v200
	v_add_u32_e32 v245, v28, v201
	ds_read_b64_tr_b16 v[28:29], v244 offset:0
	ds_read_b64_tr_b16 v[30:31], v244 offset:0x400
	ds_read_b64_tr_b16 v[240:241], v245 offset:0
	ds_read_b64_tr_b16 v[242:243], v245 offset:0x400
	v_cvt_pk_bf16_f32 v23, v0, v23
	s_waitcnt lgkmcnt(0)
	v_cvt_pk_bf16_f32 v24, v24, v25
	v_mfma_f32_32x32x16_bf16 v[96:111], v[28:31], v[18:21], v[96:111]
	v_exp_f32_e32 v0, v16
	v_exp_f32_e32 v25, v17
	v_exp_f32_e32 v26, v128
	v_exp_f32_e32 v27, v129
	v_dot2c_f32_bf16_e32 v191, 0x3f803f80, v18
	v_dot2c_f32_bf16_e32 v191, 0x3f803f80, v19
	v_dot2c_f32_bf16_e32 v191, 0x3f803f80, v20
	v_mfma_f32_32x32x16_bf16 v[112:127], v[240:243], v[18:21], v[112:127]
	v_dot2c_f32_bf16_e32 v191, 0x3f803f80, v21
	v_cvt_pk_bf16_f32 v25, v0, v25
	v_cvt_pk_bf16_f32 v26, v26, v27
	v_exp_f32_e32 v0, v130
	v_exp_f32_e32 v27, v131
	ds_read_b64_tr_b16 v[240:241], v244 offset:0x800
	ds_read_b64_tr_b16 v[242:243], v244 offset:0xc00
	ds_read_b64_tr_b16 v[18:19], v245 offset:0x800
	ds_read_b64_tr_b16 v[20:21], v245 offset:0xc00
	v_exp_f32_e32 v239, v132
	v_exp_f32_e32 v28, v133
	s_waitcnt lgkmcnt(2)
	v_mfma_f32_32x32x16_bf16 v[96:111], v[240:243], v[22:25], v[96:111]
	v_cvt_pk_bf16_f32 v27, v0, v27
	v_exp_f32_e32 v0, v134
	v_exp_f32_e32 v29, v135
	v_dot2c_f32_bf16_e32 v191, 0x3f803f80, v22
	v_dot2c_f32_bf16_e32 v191, 0x3f803f80, v23
	v_dot2c_f32_bf16_e32 v191, 0x3f803f80, v24
	v_dot2c_f32_bf16_e32 v191, 0x3f803f80, v25
	s_waitcnt lgkmcnt(0)
	v_mfma_f32_32x32x16_bf16 v[112:127], v[18:21], v[22:25], v[112:127]
	v_cvt_pk_bf16_f32 v28, v239, v28
	v_cvt_pk_bf16_f32 v29, v0, v29
	ds_read_b64_tr_b16 v[22:23], v244 offset:0x1000
	ds_read_b64_tr_b16 v[24:25], v244 offset:0x1400
	ds_read_b64_tr_b16 v[18:19], v245 offset:0x1000
	ds_read_b64_tr_b16 v[20:21], v245 offset:0x1400
	v_exp_f32_e32 v0, v136
	v_exp_f32_e32 v30, v137
	v_exp_f32_e32 v31, v138
	s_waitcnt lgkmcnt(2)
	v_mfma_f32_32x32x16_bf16 v[96:111], v[22:25], v[26:29], v[96:111]
	v_exp_f32_e32 v239, v139
	v_exp_f32_e32 v240, v140
	v_exp_f32_e32 v24, v141
	v_exp_f32_e32 v25, v142
	v_exp_f32_e32 v241, v143
	v_cvt_pk_bf16_f32 v22, v0, v30
	v_subrev_u32_e32 v0, s0, v232
	s_waitcnt lgkmcnt(0)
	v_mfma_f32_32x32x16_bf16 v[112:127], v[18:21], v[26:29], v[112:127]
	v_cvt_f32_i32_e32 v0, v0
	v_cvt_pk_bf16_f32 v23, v31, v239
	v_cvt_pk_bf16_f32 v24, v240, v24
	v_cvt_pk_bf16_f32 v25, v25, v241
	ds_read_b64_tr_b16 v[240:241], v244 offset:0x1800
	ds_read_b64_tr_b16 v[242:243], v244 offset:0x1c00
	ds_read_b64_tr_b16 v[18:19], v245 offset:0x1800
	ds_read_b64_tr_b16 v[20:21], v245 offset:0x1c00
	v_dot2c_f32_bf16_e32 v191, 0x3f803f80, v26
	v_dot2c_f32_bf16_e32 v191, 0x3f803f80, v27
	s_waitcnt lgkmcnt(2)
	v_mfma_f32_32x32x16_bf16 v[96:111], v[240:243], v[22:25], v[96:111]
	v_dot2c_f32_bf16_e32 v191, 0x3f803f80, v28
	v_fma_f32 v0, -v182, v0, v193
	v_dot2c_f32_bf16_e32 v191, 0x3f803f80, v29
	v_sub_f32_e32 v0, v0, v238
	v_dot2c_f32_bf16_e32 v191, 0x3f803f80, v22
	v_cmp_gt_f32_e32 vcc, s3, v0
	v_dot2c_f32_bf16_e32 v191, 0x3f803f80, v23
	s_waitcnt lgkmcnt(0)
	v_mfma_f32_32x32x16_bf16 v[112:127], v[18:21], v[22:25], v[112:127]
	s_cmp_eq_u64 vcc, exec
	v_dot2c_f32_bf16_e32 v191, 0x3f803f80, v24
	s_cselect_b64 s[0:1], -1, 0
	v_dot2c_f32_bf16_e32 v191, 0x3f803f80, v25
	v_cndmask_b32_e64 v239, 0, 1, s[0:1]

; #define MFMA(a, b, c) __builtin_amdgcn_mfma_f32_32x32x16_bf16((a), (b), (c), 0, 0, 0)
; DI unsigned pack2(float a, float b) { v2f f = {a, b}; return __builtin_bit_cast(unsigned, __builtin_convertvector(f, v2bf)); }
; DI float fexp2(float x) { return __builtin_amdgcn_exp2f(x); }
; template <int DV, int STEP>
; DI void pv_step(f32x16 (&ot)[DV / 32], const bf16x8 (&pk)[2][2], s16x4 (&fa)[DV / 32][2], s16x4 (&fb)[DV / 32][2], const unsigned (&a)[DV / 32]) {
;   constexpr int VP = 2 * DV, NDC = DV / 32;
;   tr_wait(fa);
;   if (STEP < 3) TrIssue<NDC, (((STEP + 1) >> 1) * 32 + ((STEP + 1) & 1) * 16) * VP, (((STEP + 1) >> 1) * 32 + ((STEP + 1) & 1) * 16 + 8) * VP>::run(fb, a);
; #pragma unroll
;   for (int dc = 0; dc < NDC; ++dc) {
;     const bf16x8 vf = __builtin_shufflevector(fa[dc][0], fa[dc][1], 0, 1, 2, 3, 4, 5, 6, 7);
;     ot[dc] = MFMA(vf, pk[STEP >> 1][STEP & 1], ot[dc]);
;   }
; }
; template <int DV, bool SEL, bool TERM> ...
;     ...
;       bf16x8 pk[2][2];
; #pragma unroll
;       for (int kb = 0; kb < 2; ++kb)
; #pragma unroll
;         for (int s2 = 0; s2 < 2; ++s2) {
;           unsigned w[4];
; #pragma unroll
;           for (int j = 0; j < 4; ++j) {
;             w[j] = pack2(fexp2(st[kb][8 * s2 + 2 * j]), fexp2(st[kb][8 * s2 + 2 * j + 1]));
;             l = dot2ones(w[j], l);
;           }
;           u32x4 v = {w[0], w[1], w[2], w[3]};
;           pk[kb][s2] = __builtin_bit_cast(bf16x8, v);
;         }
;       pv_tile<DV>(ot, pk, sb, lane);
;       if (TERM) {
;         const float bound = qb - slope2 * (float)(tqp - kp_mul * (k0 - 1)) - mref;
;         done = __all(bound < -150.f) ? 1u : 0u;
.LBB0_1498:
	v_exp_f32_e32 v0, v80
	v_exp_f32_e32 v2, v81
	v_exp_f32_e32 v3, v82
	v_exp_f32_e32 v4, v83
	v_exp_f32_e32 v5, v84
	v_exp_f32_e32 v7, v85
	v_exp_f32_e32 v8, v86
	v_exp_f32_e32 v9, v87
	s_add_i32 s1, s93, s1
	s_addk_i32 s1, 0x2000
	v_cvt_pk_bf16_f32 v2, v0, v2
	v_add_u32_e32 v0, s1, v166
	v_cvt_pk_bf16_f32 v3, v3, v4
	v_cvt_pk_bf16_f32 v4, v5, v7
	v_cvt_pk_bf16_f32 v5, v8, v9
	v_add_u32_e32 v7, v0, v167
	v_add_u32_e32 v137, v0, v168
	v_add_u32_e32 v204, v0, v169
	v_add_u32_e32 v0, v0, v170
	ds_read_b64_tr_b16 v[188:189], v7 offset:0
	ds_read_b64_tr_b16 v[190:191], v7 offset:0x800
	ds_read_b64_tr_b16 v[184:185], v137 offset:0
	ds_read_b64_tr_b16 v[186:187], v137 offset:0x800
	ds_read_b64_tr_b16 v[12:13], v204 offset:0
	ds_read_b64_tr_b16 v[14:15], v204 offset:0x800
	ds_read_b64_tr_b16 v[8:9], v0 offset:0
	ds_read_b64_tr_b16 v[10:11], v0 offset:0x800
	v_dot2c_f32_bf16_e32 v6, 0x3f803f80, v2
	s_waitcnt lgkmcnt(0)
	v_dot2c_f32_bf16_e32 v6, 0x3f803f80, v3
	v_mfma_f32_32x32x16_bf16 v[64:79], v[188:191], v[2:5], v[64:79]
	v_exp_f32_e32 v188, v92
	v_exp_f32_e32 v189, v95
	v_dot2c_f32_bf16_e32 v6, 0x3f803f80, v4
	v_dot2c_f32_bf16_e32 v6, 0x3f803f80, v5
	v_mfma_f32_32x32x16_bf16 v[48:63], v[184:187], v[2:5], v[48:63]
	v_exp_f32_e32 v184, v88
	v_exp_f32_e32 v185, v89
	v_exp_f32_e32 v186, v90
	v_exp_f32_e32 v187, v91
	v_mfma_f32_32x32x16_bf16 v[32:47], v[12:15], v[2:5], v[32:47]
	v_exp_f32_e32 v14, v93
	v_exp_f32_e32 v15, v94
	v_cvt_pk_bf16_f32 v12, v184, v185
	v_cvt_pk_bf16_f32 v13, v186, v187
	v_cvt_pk_bf16_f32 v14, v188, v14
	v_cvt_pk_bf16_f32 v15, v15, v189
	v_dot2c_f32_bf16_e32 v6, 0x3f803f80, v12
	v_mfma_f32_32x32x16_bf16 v[16:31], v[8:11], v[2:5], v[16:31]
	ds_read_b64_tr_b16 v[192:193], v7 offset:0x1000
	ds_read_b64_tr_b16 v[194:195], v7 offset:0x1800
	ds_read_b64_tr_b16 v[188:189], v137 offset:0x1000
	ds_read_b64_tr_b16 v[190:191], v137 offset:0x1800
	ds_read_b64_tr_b16 v[184:185], v204 offset:0x1000
	ds_read_b64_tr_b16 v[186:187], v204 offset:0x1800
	ds_read_b64_tr_b16 v[8:9], v0 offset:0x1000
	ds_read_b64_tr_b16 v[10:11], v0 offset:0x1800
	v_exp_f32_e32 v4, v106
	v_exp_f32_e32 v2, v104
	v_exp_f32_e32 v3, v105
	v_dot2c_f32_bf16_e32 v6, 0x3f803f80, v13
	v_dot2c_f32_bf16_e32 v6, 0x3f803f80, v14
	s_waitcnt lgkmcnt(6)
	v_mfma_f32_32x32x16_bf16 v[64:79], v[192:195], v[12:15], v[64:79]
	v_exp_f32_e32 v192, v100
	v_exp_f32_e32 v193, v103
	v_dot2c_f32_bf16_e32 v6, 0x3f803f80, v15
	s_waitcnt lgkmcnt(4)
	v_mfma_f32_32x32x16_bf16 v[48:63], v[188:191], v[12:15], v[48:63]
	v_exp_f32_e32 v188, v96
	v_exp_f32_e32 v189, v97
	v_exp_f32_e32 v190, v98
	v_exp_f32_e32 v191, v99
	s_waitcnt lgkmcnt(2)
	v_mfma_f32_32x32x16_bf16 v[32:47], v[184:187], v[12:15], v[32:47]
	v_exp_f32_e32 v186, v101
	v_exp_f32_e32 v187, v102
	v_cvt_pk_bf16_f32 v184, v188, v189
	v_cvt_pk_bf16_f32 v185, v190, v191
	v_cvt_pk_bf16_f32 v186, v192, v186
	v_cvt_pk_bf16_f32 v187, v187, v193
	v_dot2c_f32_bf16_e32 v6, 0x3f803f80, v184
	s_waitcnt lgkmcnt(0)
	v_mfma_f32_32x32x16_bf16 v[16:31], v[8:11], v[12:15], v[16:31]
	ds_read_b64_tr_b16 v[196:197], v7 offset:0x2000
	ds_read_b64_tr_b16 v[198:199], v7 offset:0x2800
	ds_read_b64_tr_b16 v[192:193], v137 offset:0x2000
	ds_read_b64_tr_b16 v[194:195], v137 offset:0x2800
	ds_read_b64_tr_b16 v[188:189], v204 offset:0x2000
	ds_read_b64_tr_b16 v[190:191], v204 offset:0x2800
	ds_read_b64_tr_b16 v[8:9], v0 offset:0x2000
	ds_read_b64_tr_b16 v[10:11], v0 offset:0x2800
	v_dot2c_f32_bf16_e32 v6, 0x3f803f80, v185
	v_dot2c_f32_bf16_e32 v6, 0x3f803f80, v186
	v_dot2c_f32_bf16_e32 v6, 0x3f803f80, v187
	s_waitcnt lgkmcnt(6)
	v_mfma_f32_32x32x16_bf16 v[64:79], v[196:199], v[184:187], v[64:79]
	s_waitcnt lgkmcnt(4)
	v_mfma_f32_32x32x16_bf16 v[48:63], v[192:195], v[184:187], v[48:63]
	v_exp_f32_e32 v192, v107
	v_exp_f32_e32 v193, v108
	v_exp_f32_e32 v194, v111
	s_waitcnt lgkmcnt(2)
	v_mfma_f32_32x32x16_bf16 v[32:47], v[188:191], v[184:187], v[32:47]
	v_exp_f32_e32 v190, v109
	v_exp_f32_e32 v191, v110
	v_cvt_pk_bf16_f32 v189, v4, v192
	v_cvt_pk_bf16_f32 v188, v2, v3
	v_cvt_pk_bf16_f32 v190, v193, v190
	v_cvt_pk_bf16_f32 v191, v191, v194
	v_dot2c_f32_bf16_e32 v6, 0x3f803f80, v188
	s_waitcnt lgkmcnt(0)
	v_mfma_f32_32x32x16_bf16 v[16:31], v[8:11], v[184:187], v[16:31]
	ds_read_b64_tr_b16 v[200:201], v7 offset:0x3000
	ds_read_b64_tr_b16 v[202:203], v7 offset:0x3800
	ds_read_b64_tr_b16 v[196:197], v137 offset:0x3000
	ds_read_b64_tr_b16 v[198:199], v137 offset:0x3800
	ds_read_b64_tr_b16 v[192:193], v204 offset:0x3000
	ds_read_b64_tr_b16 v[194:195], v204 offset:0x3800
	ds_read_b64_tr_b16 v[8:9], v0 offset:0x3000
	ds_read_b64_tr_b16 v[10:11], v0 offset:0x3800
	v_subrev_u32_e32 v0, s0, v171
	v_cvt_f32_i32_e32 v0, v0
	s_mov_b32 s0, 0xc3160000
	v_dot2c_f32_bf16_e32 v6, 0x3f803f80, v189
	v_fma_f32 v0, -v136, v0, v135
	s_waitcnt lgkmcnt(6)
	v_mfma_f32_32x32x16_bf16 v[64:79], v[200:203], v[188:191], v[64:79]
	v_sub_f32_e32 v0, v0, v183
	v_cmp_gt_f32_e32 vcc, s0, v0
	s_cmp_eq_u64 vcc, exec
	v_dot2c_f32_bf16_e32 v6, 0x3f803f80, v190
	s_cselect_b64 s[0:1], -1, 0
	v_dot2c_f32_bf16_e32 v6, 0x3f803f80, v191
	v_cndmask_b32_e64 v184, 0, 1, s[0:1]
	s_waitcnt lgkmcnt(4)
	v_mfma_f32_32x32x16_bf16 v[48:63], v[196:199], v[188:191], v[48:63]
	s_waitcnt lgkmcnt(2)
	v_mfma_f32_32x32x16_bf16 v[32:47], v[192:195], v[188:191], v[32:47]
	s_waitcnt lgkmcnt(0)
	v_mfma_f32_32x32x16_bf16 v[16:31], v[8:11], v[188:191], v[16:31]

; #define MFMA(a, b, c) __builtin_amdgcn_mfma_f32_32x32x16_bf16((a), (b), (c), 0, 0, 0)
; DI unsigned pack2(float a, float b) { v2f f = {a, b}; return __builtin_bit_cast(unsigned, __builtin_convertvector(f, v2bf)); }
; DI float fexp2(float x) { return __builtin_amdgcn_exp2f(x); }
; template <int DV, int STEP>
; DI void pv_step(f32x16 (&ot)[DV / 32], const bf16x8 (&pk)[2][2], s16x4 (&fa)[DV / 32][2], s16x4 (&fb)[DV / 32][2], const unsigned (&a)[DV / 32]) {
;   constexpr int VP = 2 * DV, NDC = DV / 32;
;   tr_wait(fa);
;   if (STEP < 3) TrIssue<NDC, (((STEP + 1) >> 1) * 32 + ((STEP + 1) & 1) * 16) * VP, (((STEP + 1) >> 1) * 32 + ((STEP + 1) & 1) * 16 + 8) * VP>::run(fb, a);
; #pragma unroll
;   for (int dc = 0; dc < NDC; ++dc) {
;     const bf16x8 vf = __builtin_shufflevector(fa[dc][0], fa[dc][1], 0, 1, 2, 3, 4, 5, 6, 7);
;     ot[dc] = MFMA(vf, pk[STEP >> 1][STEP & 1], ot[dc]);
;   }
; }
; template <int DV>
; DI void pv_tile(f32x16 (&ot)[DV / 32], const bf16x8 (&pk)[2][2], char* sb, int lane) {
;   constexpr int VP = 2 * DV, NDC = DV / 32;
;   const int h = lane >> 5, i16 = lane & 15, qq = i16 >> 2, pp = i16 & 3, blk = (lane >> 4) & 1;
;   const int qx = (DV == 128) ? qq : (qq >> 1);
;   const unsigned vb = (unsigned)(size_t)(sb + 8192) + (4 * h + qq) * VP + 32 * blk + 8 * pp;
;   unsigned a[NDC];
; #pragma unroll
;   for (int dc = 0; dc < NDC; ++dc) a[dc] = vb + ((dc ^ qx) << 6);
;   s16x4 f0[NDC][2], f1[NDC][2];
;   TrIssue<NDC, 0, 8 * VP>::run(f0, a);
;   pv_step<DV, 0>(ot, pk, f0, f1, a);
;   pv_step<DV, 1>(ot, pk, f1, f0, a);
;   pv_step<DV, 2>(ot, pk, f0, f1, a);
;   pv_step<DV, 3>(ot, pk, f1, f0, a);
; }
; template <int DV, bool SEL, bool TERM> ...
;     ...
;       bf16x8 pk[2][2];
; #pragma unroll
;       for (int kb = 0; kb < 2; ++kb)
; #pragma unroll
;         for (int s2 = 0; s2 < 2; ++s2) {
;           unsigned w[4];
; #pragma unroll
;           for (int j = 0; j < 4; ++j) {
;             w[j] = pack2(fexp2(st[kb][8 * s2 + 2 * j]), fexp2(st[kb][8 * s2 + 2 * j + 1]));
;             l = dot2ones(w[j], l);
;           }
;           u32x4 v = {w[0], w[1], w[2], w[3]};
;           pk[kb][s2] = __builtin_bit_cast(bf16x8, v);
;         }
;       pv_tile<DV>(ot, pk, sb, lane);
.LBB0_2012:
	v_exp_f32_e32 v0, v80
	v_exp_f32_e32 v2, v81
	v_exp_f32_e32 v3, v82
	v_exp_f32_e32 v4, v83
	v_exp_f32_e32 v5, v84
	v_exp_f32_e32 v6, v85
	v_exp_f32_e32 v7, v86
	v_exp_f32_e32 v8, v87
	s_add_i32 s0, s95, s0
	s_addk_i32 s0, 0x2000
	v_cvt_pk_bf16_f32 v2, v0, v2
	v_add_u32_e32 v0, s0, v160
	v_cvt_pk_bf16_f32 v3, v3, v4
	v_cvt_pk_bf16_f32 v4, v5, v6
	v_cvt_pk_bf16_f32 v5, v7, v8
	v_add_u32_e32 v14, v0, v161
	v_add_u32_e32 v15, v0, v162
	v_add_u32_e32 v133, v0, v163
	v_add_u32_e32 v0, v0, v164
	ds_read_b64_tr_b16 v[182:183], v14 offset:0
	ds_read_b64_tr_b16 v[184:185], v14 offset:0x800
	ds_read_b64_tr_b16 v[178:179], v15 offset:0
	ds_read_b64_tr_b16 v[180:181], v15 offset:0x800
	ds_read_b64_tr_b16 v[10:11], v133 offset:0
	ds_read_b64_tr_b16 v[12:13], v133 offset:0x800
	ds_read_b64_tr_b16 v[6:7], v0 offset:0
	ds_read_b64_tr_b16 v[8:9], v0 offset:0x800
	v_exp_f32_e32 v177, v88
	s_waitcnt lgkmcnt(0)
	v_dot2c_f32_bf16_e32 v165, 0x3f803f80, v2
	v_mfma_f32_32x32x16_bf16 v[64:79], v[182:185], v[2:5], v[64:79]
	v_exp_f32_e32 v182, v95
	v_dot2c_f32_bf16_e32 v165, 0x3f803f80, v3
	v_dot2c_f32_bf16_e32 v165, 0x3f803f80, v4
	v_dot2c_f32_bf16_e32 v165, 0x3f803f80, v5
	v_mfma_f32_32x32x16_bf16 v[48:63], v[178:181], v[2:5], v[48:63]
	v_exp_f32_e32 v178, v89
	v_exp_f32_e32 v179, v90
	v_exp_f32_e32 v180, v91
	v_exp_f32_e32 v181, v92
	v_mfma_f32_32x32x16_bf16 v[32:47], v[10:13], v[2:5], v[32:47]
	v_exp_f32_e32 v12, v93
	v_exp_f32_e32 v13, v94
	v_cvt_pk_bf16_f32 v10, v177, v178
	v_cvt_pk_bf16_f32 v11, v179, v180
	v_cvt_pk_bf16_f32 v12, v181, v12
	v_cvt_pk_bf16_f32 v13, v13, v182
	v_exp_f32_e32 v177, v96
	v_mfma_f32_32x32x16_bf16 v[16:31], v[6:9], v[2:5], v[16:31]
	ds_read_b64_tr_b16 v[186:187], v14 offset:0x1000
	ds_read_b64_tr_b16 v[188:189], v14 offset:0x1800
	ds_read_b64_tr_b16 v[182:183], v15 offset:0x1000
	ds_read_b64_tr_b16 v[184:185], v15 offset:0x1800
	ds_read_b64_tr_b16 v[178:179], v133 offset:0x1000
	ds_read_b64_tr_b16 v[180:181], v133 offset:0x1800
	ds_read_b64_tr_b16 v[6:7], v0 offset:0x1000
	ds_read_b64_tr_b16 v[8:9], v0 offset:0x1800
	v_dot2c_f32_bf16_e32 v165, 0x3f803f80, v10
	v_dot2c_f32_bf16_e32 v165, 0x3f803f80, v11
	v_dot2c_f32_bf16_e32 v165, 0x3f803f80, v12
	v_dot2c_f32_bf16_e32 v165, 0x3f803f80, v13
	s_waitcnt lgkmcnt(6)
	v_mfma_f32_32x32x16_bf16 v[64:79], v[186:189], v[10:13], v[64:79]
	v_exp_f32_e32 v186, v103
	s_waitcnt lgkmcnt(4)
	v_mfma_f32_32x32x16_bf16 v[48:63], v[182:185], v[10:13], v[48:63]
	v_exp_f32_e32 v182, v97
	v_exp_f32_e32 v183, v98
	v_exp_f32_e32 v184, v99
	v_exp_f32_e32 v185, v100
	s_waitcnt lgkmcnt(2)
	v_mfma_f32_32x32x16_bf16 v[32:47], v[178:181], v[10:13], v[32:47]
	v_exp_f32_e32 v180, v101
	v_exp_f32_e32 v181, v102
	v_cvt_pk_bf16_f32 v178, v177, v182
	v_cvt_pk_bf16_f32 v179, v183, v184
	v_cvt_pk_bf16_f32 v180, v185, v180
	v_cvt_pk_bf16_f32 v181, v181, v186
	v_exp_f32_e32 v177, v104
	s_waitcnt lgkmcnt(0)
	v_mfma_f32_32x32x16_bf16 v[16:31], v[6:9], v[10:13], v[16:31]
	ds_read_b64_tr_b16 v[190:191], v14 offset:0x2000
	ds_read_b64_tr_b16 v[192:193], v14 offset:0x2800
	ds_read_b64_tr_b16 v[186:187], v15 offset:0x2000
	ds_read_b64_tr_b16 v[188:189], v15 offset:0x2800
	ds_read_b64_tr_b16 v[182:183], v133 offset:0x2000
	ds_read_b64_tr_b16 v[184:185], v133 offset:0x2800
	ds_read_b64_tr_b16 v[6:7], v0 offset:0x2000
	ds_read_b64_tr_b16 v[8:9], v0 offset:0x2800
	v_dot2c_f32_bf16_e32 v165, 0x3f803f80, v178
	v_dot2c_f32_bf16_e32 v165, 0x3f803f80, v179
	v_dot2c_f32_bf16_e32 v165, 0x3f803f80, v180
	v_dot2c_f32_bf16_e32 v165, 0x3f803f80, v181
	s_waitcnt lgkmcnt(6)
	v_mfma_f32_32x32x16_bf16 v[64:79], v[190:193], v[178:181], v[64:79]
	v_exp_f32_e32 v190, v111
	s_waitcnt lgkmcnt(4)
	v_mfma_f32_32x32x16_bf16 v[48:63], v[186:189], v[178:181], v[48:63]
	v_exp_f32_e32 v186, v105
	v_exp_f32_e32 v187, v106
	v_exp_f32_e32 v188, v107
	v_exp_f32_e32 v189, v108
	s_waitcnt lgkmcnt(2)
	v_mfma_f32_32x32x16_bf16 v[32:47], v[182:185], v[178:181], v[32:47]
	v_exp_f32_e32 v184, v109
	v_exp_f32_e32 v185, v110
	v_cvt_pk_bf16_f32 v182, v177, v186
	v_cvt_pk_bf16_f32 v183, v187, v188
	v_cvt_pk_bf16_f32 v184, v189, v184
	v_cvt_pk_bf16_f32 v185, v185, v190
	v_dot2c_f32_bf16_e32 v165, 0x3f803f80, v182
	s_waitcnt lgkmcnt(0)
	v_mfma_f32_32x32x16_bf16 v[16:31], v[6:9], v[178:181], v[16:31]
	ds_read_b64_tr_b16 v[194:195], v14 offset:0x3000
	ds_read_b64_tr_b16 v[196:197], v14 offset:0x3800
	ds_read_b64_tr_b16 v[190:191], v15 offset:0x3000
	ds_read_b64_tr_b16 v[192:193], v15 offset:0x3800
	ds_read_b64_tr_b16 v[186:187], v133 offset:0x3000
	ds_read_b64_tr_b16 v[188:189], v133 offset:0x3800
	ds_read_b64_tr_b16 v[6:7], v0 offset:0x3000
	ds_read_b64_tr_b16 v[8:9], v0 offset:0x3800
	v_dot2c_f32_bf16_e32 v165, 0x3f803f80, v183
	v_dot2c_f32_bf16_e32 v165, 0x3f803f80, v184
	v_dot2c_f32_bf16_e32 v165, 0x3f803f80, v185
	s_waitcnt lgkmcnt(6)
	v_mfma_f32_32x32x16_bf16 v[64:79], v[194:197], v[182:185], v[64:79]
	s_waitcnt lgkmcnt(4)
	v_mfma_f32_32x32x16_bf16 v[48:63], v[190:193], v[182:185], v[48:63]
	s_waitcnt lgkmcnt(2)
	v_mfma_f32_32x32x16_bf16 v[32:47], v[186:189], v[182:185], v[32:47]
	s_waitcnt lgkmcnt(0)
	v_mfma_f32_32x32x16_bf16 v[16:31], v[6:9], v[182:185], v[16:31]

; #define MFMA(a, b, c) __builtin_amdgcn_mfma_f32_32x32x16_bf16((a), (b), (c), 0, 0, 0)
; DI unsigned pack2(float a, float b) { v2f f = {a, b}; return __builtin_bit_cast(unsigned, __builtin_convertvector(f, v2bf)); }
; DI float fexp2(float x) { return __builtin_amdgcn_exp2f(x); }
; template <int DV, int STEP>
; DI void pv_step(f32x16 (&ot)[DV / 32], const bf16x8 (&pk)[2][2], s16x4 (&fa)[DV / 32][2], s16x4 (&fb)[DV / 32][2], const unsigned (&a)[DV / 32]) {
;   constexpr int VP = 2 * DV, NDC = DV / 32;
;   tr_wait(fa);
;   if (STEP < 3) TrIssue<NDC, (((STEP + 1) >> 1) * 32 + ((STEP + 1) & 1) * 16) * VP, (((STEP + 1) >> 1) * 32 + ((STEP + 1) & 1) * 16 + 8) * VP>::run(fb, a);
; #pragma unroll
;   for (int dc = 0; dc < NDC; ++dc) {
;     const bf16x8 vf = __builtin_shufflevector(fa[dc][0], fa[dc][1], 0, 1, 2, 3, 4, 5, 6, 7);
;     ot[dc] = MFMA(vf, pk[STEP >> 1][STEP & 1], ot[dc]);
;   }
; }
; template <int DV>
; DI void pv_tile(f32x16 (&ot)[DV / 32], const bf16x8 (&pk)[2][2], char* sb, int lane) {
;   constexpr int VP = 2 * DV, NDC = DV / 32;
;   const int h = lane >> 5, i16 = lane & 15, qq = i16 >> 2, pp = i16 & 3, blk = (lane >> 4) & 1;
;   const int qx = (DV == 128) ? qq : (qq >> 1);
;   const unsigned vb = (unsigned)(size_t)(sb + 8192) + (4 * h + qq) * VP + 32 * blk + 8 * pp;
;   unsigned a[NDC];
; #pragma unroll
;   for (int dc = 0; dc < NDC; ++dc) a[dc] = vb + ((dc ^ qx) << 6);
;   s16x4 f0[NDC][2], f1[NDC][2];
;   TrIssue<NDC, 0, 8 * VP>::run(f0, a);
;   pv_step<DV, 0>(ot, pk, f0, f1, a);
;   pv_step<DV, 1>(ot, pk, f1, f0, a);
;   pv_step<DV, 2>(ot, pk, f0, f1, a);
;   pv_step<DV, 3>(ot, pk, f1, f0, a);
; }
; template <int DV, bool SEL, bool TERM> ...
;     ...
;       bf16x8 pk[2][2];
; #pragma unroll
;       for (int kb = 0; kb < 2; ++kb)
; #pragma unroll
;         for (int s2 = 0; s2 < 2; ++s2) {
;           unsigned w[4];
; #pragma unroll
;           for (int j = 0; j < 4; ++j) {
;             w[j] = pack2(fexp2(st[kb][8 * s2 + 2 * j]), fexp2(st[kb][8 * s2 + 2 * j + 1]));
;             l = dot2ones(w[j], l);
;           }
;           u32x4 v = {w[0], w[1], w[2], w[3]};
;           pk[kb][s2] = __builtin_bit_cast(bf16x8, v);
;         }
;       pv_tile<DV>(ot, pk, sb, lane);
.LBB0_2101:
	v_exp_f32_e32 v0, v80
	v_exp_f32_e32 v2, v81
	v_exp_f32_e32 v3, v82
	v_exp_f32_e32 v4, v83
	v_exp_f32_e32 v5, v84
	v_exp_f32_e32 v6, v85
	v_exp_f32_e32 v7, v86
	v_exp_f32_e32 v8, v87
	s_add_i32 s0, s19, s0
	s_addk_i32 s0, 0x2000
	v_cvt_pk_bf16_f32 v2, v0, v2
	v_add_u32_e32 v0, s0, v169
	v_cvt_pk_bf16_f32 v3, v3, v4
	v_cvt_pk_bf16_f32 v4, v5, v6
	v_cvt_pk_bf16_f32 v5, v7, v8
	v_add_u32_e32 v14, v0, v170
	v_add_u32_e32 v15, v0, v171
	v_add_u32_e32 v137, v0, v172
	v_add_u32_e32 v0, v0, v173
	ds_read_b64_tr_b16 v[190:191], v14 offset:0
	ds_read_b64_tr_b16 v[192:193], v14 offset:0x800
	ds_read_b64_tr_b16 v[186:187], v15 offset:0
	ds_read_b64_tr_b16 v[188:189], v15 offset:0x800
	ds_read_b64_tr_b16 v[10:11], v137 offset:0
	ds_read_b64_tr_b16 v[12:13], v137 offset:0x800
	ds_read_b64_tr_b16 v[6:7], v0 offset:0
	ds_read_b64_tr_b16 v[8:9], v0 offset:0x800
	v_exp_f32_e32 v185, v88
	s_waitcnt lgkmcnt(0)
	v_dot2c_f32_bf16_e32 v155, 0x3f803f80, v2
	v_mfma_f32_32x32x16_bf16 v[64:79], v[190:193], v[2:5], v[64:79]
	v_exp_f32_e32 v190, v95
	v_dot2c_f32_bf16_e32 v155, 0x3f803f80, v3
	v_dot2c_f32_bf16_e32 v155, 0x3f803f80, v4
	v_dot2c_f32_bf16_e32 v155, 0x3f803f80, v5
	v_mfma_f32_32x32x16_bf16 v[48:63], v[186:189], v[2:5], v[48:63]
	v_exp_f32_e32 v186, v89
	v_exp_f32_e32 v187, v90
	v_exp_f32_e32 v188, v91
	v_exp_f32_e32 v189, v92
	v_mfma_f32_32x32x16_bf16 v[32:47], v[10:13], v[2:5], v[32:47]
	v_exp_f32_e32 v12, v93
	v_exp_f32_e32 v13, v94
	v_cvt_pk_bf16_f32 v10, v185, v186
	v_cvt_pk_bf16_f32 v11, v187, v188
	v_cvt_pk_bf16_f32 v12, v189, v12
	v_cvt_pk_bf16_f32 v13, v13, v190
	v_exp_f32_e32 v185, v96
	v_mfma_f32_32x32x16_bf16 v[16:31], v[6:9], v[2:5], v[16:31]
	ds_read_b64_tr_b16 v[194:195], v14 offset:0x1000
	ds_read_b64_tr_b16 v[196:197], v14 offset:0x1800
	ds_read_b64_tr_b16 v[190:191], v15 offset:0x1000
	ds_read_b64_tr_b16 v[192:193], v15 offset:0x1800
	ds_read_b64_tr_b16 v[186:187], v137 offset:0x1000
	ds_read_b64_tr_b16 v[188:189], v137 offset:0x1800
	ds_read_b64_tr_b16 v[6:7], v0 offset:0x1000
	ds_read_b64_tr_b16 v[8:9], v0 offset:0x1800
	v_dot2c_f32_bf16_e32 v155, 0x3f803f80, v10
	v_dot2c_f32_bf16_e32 v155, 0x3f803f80, v11
	v_dot2c_f32_bf16_e32 v155, 0x3f803f80, v12
	v_dot2c_f32_bf16_e32 v155, 0x3f803f80, v13
	s_waitcnt lgkmcnt(6)
	v_mfma_f32_32x32x16_bf16 v[64:79], v[194:197], v[10:13], v[64:79]
	v_exp_f32_e32 v194, v103
	s_waitcnt lgkmcnt(4)
	v_mfma_f32_32x32x16_bf16 v[48:63], v[190:193], v[10:13], v[48:63]
	v_exp_f32_e32 v190, v97
	v_exp_f32_e32 v191, v98
	v_exp_f32_e32 v192, v99
	v_exp_f32_e32 v193, v100
	s_waitcnt lgkmcnt(2)
	v_mfma_f32_32x32x16_bf16 v[32:47], v[186:189], v[10:13], v[32:47]
	v_exp_f32_e32 v188, v101
	v_exp_f32_e32 v189, v102
	v_cvt_pk_bf16_f32 v186, v185, v190
	v_cvt_pk_bf16_f32 v187, v191, v192
	v_cvt_pk_bf16_f32 v188, v193, v188
	v_cvt_pk_bf16_f32 v189, v189, v194
	v_exp_f32_e32 v185, v104
	s_waitcnt lgkmcnt(0)
	v_mfma_f32_32x32x16_bf16 v[16:31], v[6:9], v[10:13], v[16:31]
	ds_read_b64_tr_b16 v[198:199], v14 offset:0x2000
	ds_read_b64_tr_b16 v[200:201], v14 offset:0x2800
	ds_read_b64_tr_b16 v[194:195], v15 offset:0x2000
	ds_read_b64_tr_b16 v[196:197], v15 offset:0x2800
	ds_read_b64_tr_b16 v[190:191], v137 offset:0x2000
	ds_read_b64_tr_b16 v[192:193], v137 offset:0x2800
	ds_read_b64_tr_b16 v[6:7], v0 offset:0x2000
	ds_read_b64_tr_b16 v[8:9], v0 offset:0x2800
	v_dot2c_f32_bf16_e32 v155, 0x3f803f80, v186
	v_dot2c_f32_bf16_e32 v155, 0x3f803f80, v187
	v_dot2c_f32_bf16_e32 v155, 0x3f803f80, v188
	v_dot2c_f32_bf16_e32 v155, 0x3f803f80, v189
	s_waitcnt lgkmcnt(6)
	v_mfma_f32_32x32x16_bf16 v[64:79], v[198:201], v[186:189], v[64:79]
	v_exp_f32_e32 v198, v111
	s_waitcnt lgkmcnt(4)
	v_mfma_f32_32x32x16_bf16 v[48:63], v[194:197], v[186:189], v[48:63]
	v_exp_f32_e32 v194, v105
	v_exp_f32_e32 v195, v106
	v_exp_f32_e32 v196, v107
	v_exp_f32_e32 v197, v108
	s_waitcnt lgkmcnt(2)
	v_mfma_f32_32x32x16_bf16 v[32:47], v[190:193], v[186:189], v[32:47]
	v_exp_f32_e32 v192, v109
	v_exp_f32_e32 v193, v110
	v_cvt_pk_bf16_f32 v190, v185, v194
	v_cvt_pk_bf16_f32 v191, v195, v196
	v_cvt_pk_bf16_f32 v192, v197, v192
	v_cvt_pk_bf16_f32 v193, v193, v198
	v_dot2c_f32_bf16_e32 v155, 0x3f803f80, v190
	s_waitcnt lgkmcnt(0)
	v_mfma_f32_32x32x16_bf16 v[16:31], v[6:9], v[186:189], v[16:31]
	ds_read_b64_tr_b16 v[202:203], v14 offset:0x3000
	ds_read_b64_tr_b16 v[204:205], v14 offset:0x3800
	ds_read_b64_tr_b16 v[198:199], v15 offset:0x3000
	ds_read_b64_tr_b16 v[200:201], v15 offset:0x3800
	ds_read_b64_tr_b16 v[194:195], v137 offset:0x3000
	ds_read_b64_tr_b16 v[196:197], v137 offset:0x3800
	ds_read_b64_tr_b16 v[6:7], v0 offset:0x3000
	ds_read_b64_tr_b16 v[8:9], v0 offset:0x3800
	v_dot2c_f32_bf16_e32 v155, 0x3f803f80, v191
	v_dot2c_f32_bf16_e32 v155, 0x3f803f80, v192
	v_dot2c_f32_bf16_e32 v155, 0x3f803f80, v193
	s_waitcnt lgkmcnt(6)
	v_mfma_f32_32x32x16_bf16 v[64:79], v[202:205], v[190:193], v[64:79]
	s_waitcnt lgkmcnt(4)
	v_mfma_f32_32x32x16_bf16 v[48:63], v[198:201], v[190:193], v[48:63]
	s_waitcnt lgkmcnt(2)
	v_mfma_f32_32x32x16_bf16 v[32:47], v[194:197], v[190:193], v[32:47]
	s_waitcnt lgkmcnt(0)
	v_mfma_f32_32x32x16_bf16 v[16:31], v[6:9], v[190:193], v[16:31]

; #define MFMA(a, b, c) __builtin_amdgcn_mfma_f32_32x32x16_bf16((a), (b), (c), 0, 0, 0)
; DI unsigned pack2(float a, float b) { v2f f = {a, b}; return __builtin_bit_cast(unsigned, __builtin_convertvector(f, v2bf)); }
; DI float fexp2(float x) { return __builtin_amdgcn_exp2f(x); }
; template <int DV, int STEP>
; DI void pv_step(f32x16 (&ot)[DV / 32], const bf16x8 (&pk)[2][2], s16x4 (&fa)[DV / 32][2], s16x4 (&fb)[DV / 32][2], const unsigned (&a)[DV / 32]) {
;   constexpr int VP = 2 * DV, NDC = DV / 32;
;   tr_wait(fa);
;   if (STEP < 3) TrIssue<NDC, (((STEP + 1) >> 1) * 32 + ((STEP + 1) & 1) * 16) * VP, (((STEP + 1) >> 1) * 32 + ((STEP + 1) & 1) * 16 + 8) * VP>::run(fb, a);
; #pragma unroll
;   for (int dc = 0; dc < NDC; ++dc) {
;     const bf16x8 vf = __builtin_shufflevector(fa[dc][0], fa[dc][1], 0, 1, 2, 3, 4, 5, 6, 7);
;     ot[dc] = MFMA(vf, pk[STEP >> 1][STEP & 1], ot[dc]);
;   }
; }
; template <int DV>
; DI void pv_tile(f32x16 (&ot)[DV / 32], const bf16x8 (&pk)[2][2], char* sb, int lane) {
;   constexpr int VP = 2 * DV, NDC = DV / 32;
;   const int h = lane >> 5, i16 = lane & 15, qq = i16 >> 2, pp = i16 & 3, blk = (lane >> 4) & 1;
;   const int qx = (DV == 128) ? qq : (qq >> 1);
;   const unsigned vb = (unsigned)(size_t)(sb + 8192) + (4 * h + qq) * VP + 32 * blk + 8 * pp;
;   unsigned a[NDC];
; #pragma unroll
;   for (int dc = 0; dc < NDC; ++dc) a[dc] = vb + ((dc ^ qx) << 6);
;   s16x4 f0[NDC][2], f1[NDC][2];
;   TrIssue<NDC, 0, 8 * VP>::run(f0, a);
;   pv_step<DV, 0>(ot, pk, f0, f1, a);
;   pv_step<DV, 1>(ot, pk, f1, f0, a);
;   pv_step<DV, 2>(ot, pk, f0, f1, a);
;   pv_step<DV, 3>(ot, pk, f1, f0, a);
; }
; template <int DV, bool SEL, bool TERM> ...
;     ...
;       bf16x8 pk[2][2];
; #pragma unroll
;       for (int kb = 0; kb < 2; ++kb)
; #pragma unroll
;         for (int s2 = 0; s2 < 2; ++s2) {
;           unsigned w[4];
; #pragma unroll
;           for (int j = 0; j < 4; ++j) {
;             w[j] = pack2(fexp2(st[kb][8 * s2 + 2 * j]), fexp2(st[kb][8 * s2 + 2 * j + 1]));
;             l = dot2ones(w[j], l);
;           }
;           u32x4 v = {w[0], w[1], w[2], w[3]};
;           pk[kb][s2] = __builtin_bit_cast(bf16x8, v);
;         }
;       pv_tile<DV>(ot, pk, sb, lane);
.LBB0_2125:
	v_exp_f32_e32 v0, v80
	v_exp_f32_e32 v15, v81
	v_exp_f32_e32 v117, v82
	v_exp_f32_e32 v118, v83
	v_exp_f32_e32 v119, v84
	v_exp_f32_e32 v169, v85
	v_exp_f32_e32 v170, v86
	v_exp_f32_e32 v171, v87
	s_add_i32 s0, s17, s0
	s_addk_i32 s0, 0x2000
	v_cvt_pk_bf16_f32 v116, v0, v15
	v_add_u32_e32 v0, s0, v144
	v_cvt_pk_bf16_f32 v117, v117, v118
	v_cvt_pk_bf16_f32 v118, v119, v169
	v_cvt_pk_bf16_f32 v119, v170, v171
	v_add_u32_e32 v15, v0, v145
	v_add_u32_e32 v169, v0, v146
	v_add_u32_e32 v198, v0, v147
	v_add_u32_e32 v0, v0, v157
	ds_read_b64_tr_b16 v[182:183], v15 offset:0
	ds_read_b64_tr_b16 v[184:185], v15 offset:0x800
	ds_read_b64_tr_b16 v[178:179], v169 offset:0
	ds_read_b64_tr_b16 v[180:181], v169 offset:0x800
	ds_read_b64_tr_b16 v[174:175], v198 offset:0
	ds_read_b64_tr_b16 v[176:177], v198 offset:0x800
	ds_read_b64_tr_b16 v[170:171], v0 offset:0
	ds_read_b64_tr_b16 v[172:173], v0 offset:0x800
	v_dot2c_f32_bf16_e32 v155, 0x3f803f80, v116
	s_waitcnt lgkmcnt(0)
	v_dot2c_f32_bf16_e32 v155, 0x3f803f80, v117
	v_mfma_f32_32x32x16_bf16 v[64:79], v[182:185], v[116:119], v[64:79]
	v_exp_f32_e32 v182, v92
	v_exp_f32_e32 v183, v95
	v_dot2c_f32_bf16_e32 v155, 0x3f803f80, v118
	v_dot2c_f32_bf16_e32 v155, 0x3f803f80, v119
	v_mfma_f32_32x32x16_bf16 v[48:63], v[178:181], v[116:119], v[48:63]
	v_exp_f32_e32 v178, v88
	v_exp_f32_e32 v179, v89
	v_exp_f32_e32 v180, v90
	v_exp_f32_e32 v181, v91
	v_mfma_f32_32x32x16_bf16 v[32:47], v[174:177], v[116:119], v[32:47]
	v_exp_f32_e32 v176, v93
	v_exp_f32_e32 v177, v94
	v_cvt_pk_bf16_f32 v174, v178, v179
	v_cvt_pk_bf16_f32 v175, v180, v181
	v_cvt_pk_bf16_f32 v176, v182, v176
	v_cvt_pk_bf16_f32 v177, v177, v183
	v_dot2c_f32_bf16_e32 v155, 0x3f803f80, v174
	v_mfma_f32_32x32x16_bf16 v[16:31], v[170:173], v[116:119], v[16:31]
	ds_read_b64_tr_b16 v[186:187], v15 offset:0x1000
	ds_read_b64_tr_b16 v[188:189], v15 offset:0x1800
	ds_read_b64_tr_b16 v[182:183], v169 offset:0x1000
	ds_read_b64_tr_b16 v[184:185], v169 offset:0x1800
	ds_read_b64_tr_b16 v[178:179], v198 offset:0x1000
	ds_read_b64_tr_b16 v[180:181], v198 offset:0x1800
	ds_read_b64_tr_b16 v[170:171], v0 offset:0x1000
	ds_read_b64_tr_b16 v[172:173], v0 offset:0x1800
	v_dot2c_f32_bf16_e32 v155, 0x3f803f80, v175
	v_dot2c_f32_bf16_e32 v155, 0x3f803f80, v176
	v_dot2c_f32_bf16_e32 v155, 0x3f803f80, v177
	s_waitcnt lgkmcnt(6)
	v_mfma_f32_32x32x16_bf16 v[64:79], v[186:189], v[174:177], v[64:79]
	v_exp_f32_e32 v186, v100
	v_exp_f32_e32 v187, v103
	s_waitcnt lgkmcnt(4)
	v_mfma_f32_32x32x16_bf16 v[48:63], v[182:185], v[174:177], v[48:63]
	v_exp_f32_e32 v182, v96
	v_exp_f32_e32 v183, v97
	v_exp_f32_e32 v184, v98
	v_exp_f32_e32 v185, v99
	s_waitcnt lgkmcnt(2)
	v_mfma_f32_32x32x16_bf16 v[32:47], v[178:181], v[174:177], v[32:47]
	v_exp_f32_e32 v180, v101
	v_exp_f32_e32 v181, v102
	v_cvt_pk_bf16_f32 v178, v182, v183
	v_cvt_pk_bf16_f32 v179, v184, v185
	v_cvt_pk_bf16_f32 v180, v186, v180
	v_cvt_pk_bf16_f32 v181, v181, v187
	v_dot2c_f32_bf16_e32 v155, 0x3f803f80, v178
	s_waitcnt lgkmcnt(0)
	v_mfma_f32_32x32x16_bf16 v[16:31], v[170:173], v[174:177], v[16:31]
	ds_read_b64_tr_b16 v[190:191], v15 offset:0x2000
	ds_read_b64_tr_b16 v[192:193], v15 offset:0x2800
	ds_read_b64_tr_b16 v[186:187], v169 offset:0x2000
	ds_read_b64_tr_b16 v[188:189], v169 offset:0x2800
	ds_read_b64_tr_b16 v[182:183], v198 offset:0x2000
	ds_read_b64_tr_b16 v[184:185], v198 offset:0x2800
	ds_read_b64_tr_b16 v[170:171], v0 offset:0x2000
	ds_read_b64_tr_b16 v[172:173], v0 offset:0x2800
	v_dot2c_f32_bf16_e32 v155, 0x3f803f80, v179
	v_dot2c_f32_bf16_e32 v155, 0x3f803f80, v180
	v_dot2c_f32_bf16_e32 v155, 0x3f803f80, v181
	s_waitcnt lgkmcnt(6)
	v_mfma_f32_32x32x16_bf16 v[64:79], v[190:193], v[178:181], v[64:79]
	v_exp_f32_e32 v190, v108
	v_exp_f32_e32 v191, v111
	s_waitcnt lgkmcnt(4)
	v_mfma_f32_32x32x16_bf16 v[48:63], v[186:189], v[178:181], v[48:63]
	v_exp_f32_e32 v186, v104
	v_exp_f32_e32 v187, v105
	v_exp_f32_e32 v188, v106
	v_exp_f32_e32 v189, v107
	s_waitcnt lgkmcnt(2)
	v_mfma_f32_32x32x16_bf16 v[32:47], v[182:185], v[178:181], v[32:47]
	v_exp_f32_e32 v184, v109
	v_exp_f32_e32 v185, v110
	v_cvt_pk_bf16_f32 v182, v186, v187
	v_cvt_pk_bf16_f32 v183, v188, v189
	v_cvt_pk_bf16_f32 v184, v190, v184
	v_cvt_pk_bf16_f32 v185, v185, v191
	v_dot2c_f32_bf16_e32 v155, 0x3f803f80, v182
	s_waitcnt lgkmcnt(0)
	v_mfma_f32_32x32x16_bf16 v[16:31], v[170:173], v[178:181], v[16:31]
	ds_read_b64_tr_b16 v[194:195], v15 offset:0x3000
	ds_read_b64_tr_b16 v[196:197], v15 offset:0x3800
	ds_read_b64_tr_b16 v[190:191], v169 offset:0x3000
	ds_read_b64_tr_b16 v[192:193], v169 offset:0x3800
	ds_read_b64_tr_b16 v[186:187], v198 offset:0x3000
	ds_read_b64_tr_b16 v[188:189], v198 offset:0x3800
	ds_read_b64_tr_b16 v[170:171], v0 offset:0x3000
	ds_read_b64_tr_b16 v[172:173], v0 offset:0x3800
	v_dot2c_f32_bf16_e32 v155, 0x3f803f80, v183
	v_dot2c_f32_bf16_e32 v155, 0x3f803f80, v184
	v_dot2c_f32_bf16_e32 v155, 0x3f803f80, v185
	s_waitcnt lgkmcnt(6)
	v_mfma_f32_32x32x16_bf16 v[64:79], v[194:197], v[182:185], v[64:79]
	s_waitcnt lgkmcnt(4)
	v_mfma_f32_32x32x16_bf16 v[48:63], v[190:193], v[182:185], v[48:63]
	s_waitcnt lgkmcnt(2)
	v_mfma_f32_32x32x16_bf16 v[32:47], v[186:189], v[182:185], v[32:47]
	s_waitcnt lgkmcnt(0)
	v_mfma_f32_32x32x16_bf16 v[16:31], v[170:173], v[182:185], v[16:31]

; #define MFMA(a, b, c) __builtin_amdgcn_mfma_f32_32x32x16_bf16((a), (b), (c), 0, 0, 0)
; DI float fexp(float x) { return __builtin_amdgcn_exp2f(x * LOG2E); }
; DI float flog(float x) { return __builtin_amdgcn_logf(x) * 0.6931471805599453f; }
; DI void qk_acc(f32x16 (&st)[2], const bf16x8 (&qf)[4], const char* sb, const int (&foff)[4]) {
; #pragma unroll
;   for (int kb = 0; kb < 2; ++kb)
; #pragma unroll
;     for (int ks = 0; ks < 4; ++ks) {
;       const bf16x8 kf = *(const bf16x8*)(sb + kb * 4096 + foff[ks]);
;       st[kb] = MFMA(kf, qf[ks], st[kb]);
;     }
; }
; DI void stick_attn_phase(const Params& p, char* smem) {
;     ...
;       if (k0 < q0 + 31) {
;         const bool need_mask = (k0 + 63 >= q0);
;         f32x16 st[2];
; #pragma unroll
;         for (int kb = 0; kb < 2; ++kb)
; #pragma unroll
;           for (int i = 0; i < 16; ++i) st[kb][i] = 0.f;
;         qk_acc(st, qf, sb, foff);
;         bf16x8 pk[2][2];
; #pragma unroll
;     ...
;           float lo[16], cs[4], pc[4];
; #pragma unroll
;           for (int i = 0; i < 16; ++i) {
;             const float z = st[kb][i];
;             const float sp = fmaxf(z, 0.f) + flog(1.f + fexp(-fabsf(z)));
;             bool valid = true;
;             if (need_mask) valid = (k0 + kb * 32 + (i & 3) + 8 * (i >> 2) + 4 * h) < tq;
;             lo[i] = valid ? -sp : 0.f;
;             st[kb][i] = valid ? z : -INFINITY;
;           }
.LBB0_2617:
	s_sub_i32 s0, s35, 63
	v_cmp_lt_i32_e32 vcc, s0, v116
	s_and_saveexec_b64 s[26:27], vcc
	s_cbranch_execz .LBB0_2606
	s_mul_hi_u32 s0, s37, 0xaaaaaaab
	s_lshr_b32 s0, s0, 1
	s_mul_i32 s0, s0, 0xffff4000
	s_add_i32 s0, s36, s0
	v_add_u32_e32 v0, s0, v126
	ds_read_b128 v[2:5], v0
	ds_read_b128 v[6:9], v0 offset:4096
	v_add_u32_e32 v0, s0, v127
	v_add_u32_e32 v10, s0, v125
	v_cmp_lt_i32_e32 vcc, s35, v113
	s_waitcnt lgkmcnt(0)
	v_mfma_f32_32x32x16_bf16 v[48:63], v[2:5], v[80:83], 0
	ds_read_b128 v[2:5], v0 offset:4096
	v_mfma_f32_32x32x16_bf16 v[64:79], v[6:9], v[80:83], 0
	s_waitcnt lgkmcnt(0)
	v_mfma_f32_32x32x16_bf16 v[64:79], v[2:5], v[84:87], v[64:79]
	ds_read_b128 v[2:5], v10 offset:4096
	ds_read_b128 v[6:9], v0
	ds_read_b128 v[10:13], v10
	v_add_u32_e32 v0, s0, v124
	ds_read_b128 v[128:131], v0
	ds_read_b128 v[132:135], v0 offset:4096
	v_add_u32_e32 v0, s35, v115
	s_addk_i32 s0, 0x2000
	s_waitcnt lgkmcnt(0)
	v_mfma_f32_32x32x16_bf16 v[64:79], v[2:5], v[88:91], v[64:79]
	v_subrev_u32_e32 v4, 30, v0
	v_cmp_lt_i32_e64 s[10:11], v4, v98
	v_subrev_u32_e32 v3, 31, v0
	v_cmp_lt_i32_e64 s[8:9], v3, v98
	s_or_b64 s[8:9], vcc, s[8:9]
	v_subrev_u32_e32 v5, 29, v0
	v_subrev_u32_e32 v2, 63, v0
	v_mfma_f32_32x32x16_bf16 v[64:79], v[132:135], v[92:95], v[64:79]
	v_mfma_f32_32x32x16_bf16 v[48:63], v[6:9], v[84:87], v[48:63]
	s_nop 10
	v_mul_f32_e64 v4, |v64|, s29
	v_exp_f32_e32 v4, v4
	v_mul_f32_e64 v15, |v65|, s29
	v_max_f32_e32 v3, v64, v64
	v_exp_f32_e32 v6, v15
	v_add_f32_e32 v4, 1.0, v4
	v_log_f32_e32 v4, v4
	v_max_f32_e32 v3, 0, v3
	v_mul_f32_e64 v132, |v66|, s29
	v_exp_f32_e32 v7, v132
	v_fmac_f32_e32 v3, 0x3f317218, v4
	v_cndmask_b32_e64 v4, 0, -v3, s[8:9]
	v_mul_f32_e64 v3, |v67|, s29
	v_add_f32_e32 v6, 1.0, v6
	v_exp_f32_e32 v3, v3
	v_log_f32_e32 v6, v6
	v_mfma_f32_32x32x16_bf16 v[48:63], v[10:13], v[88:91], v[48:63]
	v_max_f32_e32 v14, v65, v65
	v_max_f32_e32 v8, 0, v14
	v_add_f32_e32 v7, 1.0, v7
	v_add_f32_e32 v3, 1.0, v3
	v_log_f32_e32 v7, v7
	v_fmac_f32_e32 v8, 0x3f317218, v6
	v_log_f32_e32 v3, v3
	v_mul_f32_e64 v6, |v68|, s29
	v_cndmask_b32_e64 v10, v112, v64, s[8:9]
	s_or_b64 s[8:9], vcc, s[10:11]
	v_exp_f32_e32 v6, v6
	v_max_f32_e32 v108, v66, v66
	v_cndmask_b32_e64 v11, 0, -v8, s[8:9]
	v_cndmask_b32_e64 v14, v112, v65, s[8:9]
	v_cmp_lt_i32_e64 s[8:9], v5, v98
	v_max_f32_e32 v5, v67, v67
	v_max_f32_e32 v9, 0, v108
	v_max_f32_e32 v5, 0, v5
	v_fmac_f32_e32 v9, 0x3f317218, v7
	s_or_b64 s[8:9], vcc, s[8:9]
	v_fmac_f32_e32 v5, 0x3f317218, v3
	v_subrev_u32_e32 v3, 28, v0
	v_mfma_f32_32x32x16_bf16 v[48:63], v[128:131], v[92:95], v[48:63]
	v_cndmask_b32_e64 v15, 0, -v9, s[8:9]
	v_cndmask_b32_e64 v128, v112, v66, s[8:9]
	v_cmp_lt_i32_e64 s[8:9], v3, v98
	v_add_f32_e32 v3, 1.0, v6
	v_log_f32_e32 v3, v3
	v_mul_f32_e64 v6, |v69|, s29
	s_or_b64 s[8:9], vcc, s[8:9]
	v_exp_f32_e32 v6, v6
	v_cndmask_b32_e64 v66, 0, -v5, s[8:9]
	v_max_f32_e32 v5, v68, v68
	v_max_f32_e32 v5, 0, v5
	v_fmac_f32_e32 v5, 0x3f317218, v3
	v_subrev_u32_e32 v3, 23, v0
	v_cndmask_b32_e64 v129, v112, v67, s[8:9]
	v_cmp_lt_i32_e64 s[8:9], v3, v98
	v_add_f32_e32 v3, 1.0, v6
	v_log_f32_e32 v3, v3
	v_mul_f32_e64 v6, |v70|, s29
	s_or_b64 s[8:9], vcc, s[8:9]
	v_exp_f32_e32 v6, v6
	v_cndmask_b32_e64 v130, 0, -v5, s[8:9]
	v_max_f32_e32 v5, v69, v69
	v_max_f32_e32 v5, 0, v5
	v_fmac_f32_e32 v5, 0x3f317218, v3
	v_subrev_u32_e32 v3, 22, v0
	v_cndmask_b32_e64 v131, v112, v68, s[8:9]
	v_cmp_lt_i32_e64 s[8:9], v3, v98
	v_add_f32_e32 v3, 1.0, v6
	v_log_f32_e32 v3, v3
	v_mul_f32_e64 v6, |v71|, s29
	s_or_b64 s[8:9], vcc, s[8:9]
	v_exp_f32_e32 v6, v6
	v_cndmask_b32_e64 v132, 0, -v5, s[8:9]
	v_max_f32_e32 v5, v70, v70
	v_max_f32_e32 v5, 0, v5
	v_fmac_f32_e32 v5, 0x3f317218, v3
	v_subrev_u32_e32 v3, 21, v0
	v_cndmask_b32_e64 v133, v112, v69, s[8:9]
	v_cmp_lt_i32_e64 s[8:9], v3, v98
	v_add_f32_e32 v3, 1.0, v6
	v_log_f32_e32 v3, v3
	v_mul_f32_e64 v6, |v72|, s29
	s_or_b64 s[8:9], vcc, s[8:9]
	v_exp_f32_e32 v6, v6
	v_cndmask_b32_e64 v134, 0, -v5, s[8:9]
	v_max_f32_e32 v5, v71, v71
	v_max_f32_e32 v5, 0, v5
	v_fmac_f32_e32 v5, 0x3f317218, v3
	v_subrev_u32_e32 v3, 20, v0
	v_cndmask_b32_e64 v135, v112, v70, s[8:9]
	v_cmp_lt_i32_e64 s[8:9], v3, v98
	v_add_f32_e32 v3, 1.0, v6
	v_log_f32_e32 v3, v3
	v_mul_f32_e64 v6, |v73|, s29
	s_or_b64 s[8:9], vcc, s[8:9]
	v_exp_f32_e32 v7, v6
	v_cndmask_b32_e64 v136, 0, -v5, s[8:9]
	v_max_f32_e32 v5, v72, v72
	v_max_f32_e32 v5, 0, v5
	v_fmac_f32_e32 v5, 0x3f317218, v3
	v_add_u32_e32 v3, -15, v0
	v_cndmask_b32_e64 v137, v112, v71, s[8:9]
	v_cmp_lt_i32_e64 s[8:9], v3, v98
	v_add_f32_e32 v3, 1.0, v7
	v_log_f32_e32 v3, v3
	v_mul_f32_e64 v7, |v74|, s29
	s_or_b64 s[8:9], vcc, s[8:9]
	v_exp_f32_e32 v7, v7
	v_cndmask_b32_e64 v6, 0, -v5, s[8:9]
	v_max_f32_e32 v5, v73, v73
	v_max_f32_e32 v5, 0, v5
	v_fmac_f32_e32 v5, 0x3f317218, v3
	v_add_u32_e32 v3, -14, v0
	v_cndmask_b32_e64 v13, v112, v72, s[8:9]
	v_cmp_lt_i32_e64 s[8:9], v3, v98
	v_add_f32_e32 v3, 1.0, v7
	v_log_f32_e32 v3, v3
	v_mul_f32_e64 v7, |v75|, s29
	s_or_b64 s[8:9], vcc, s[8:9]
	v_exp_f32_e32 v7, v7
	v_cndmask_b32_e64 v8, 0, -v5, s[8:9]
	v_max_f32_e32 v5, v74, v74
	v_max_f32_e32 v5, 0, v5
	v_fmac_f32_e32 v5, 0x3f317218, v3
	v_add_u32_e32 v3, -13, v0
	v_cndmask_b32_e64 v64, v112, v73, s[8:9]
	v_cmp_lt_i32_e64 s[8:9], v3, v98
	v_add_f32_e32 v3, 1.0, v7
	v_log_f32_e32 v3, v3
	v_mul_f32_e64 v7, |v76|, s29
	s_or_b64 s[8:9], vcc, s[8:9]
	v_exp_f32_e32 v7, v7
	v_cndmask_b32_e64 v65, 0, -v5, s[8:9]
	v_max_f32_e32 v5, v75, v75
	v_max_f32_e32 v5, 0, v5
	v_fmac_f32_e32 v5, 0x3f317218, v3
	v_add_u32_e32 v3, -12, v0
	v_cndmask_b32_e64 v67, v112, v74, s[8:9]
	v_cmp_lt_i32_e64 s[8:9], v3, v98
	v_add_f32_e32 v3, 1.0, v7
; DI float fexp(float x) { return __builtin_amdgcn_exp2f(x * LOG2E); }
; DI float flog(float x) { return __builtin_amdgcn_logf(x) * 0.6931471805599453f; }
; DI void stick_attn_phase(const Params& p, char* smem) {
;     ...
;           float lo[16], cs[4], pc[4];
; #pragma unroll
;           for (int i = 0; i < 16; ++i) {
;             const float z = st[kb][i];
;             const float sp = fmaxf(z, 0.f) + flog(1.f + fexp(-fabsf(z)));
;             bool valid = true;
;             if (need_mask) valid = (k0 + kb * 32 + (i & 3) + 8 * (i >> 2) + 4 * h) < tq;
;             lo[i] = valid ? -sp : 0.f;
;             st[kb][i] = valid ? z : -INFINITY;
;           }
; #pragma unroll
;           for (int g4 = 0; g4 < 4; ++g4) { cs[g4] = (lo[4 * g4] + lo[4 * g4 + 1]) + (lo[4 * g4 + 2] + lo[4 * g4 + 3]); pc[g4] = xhalf(cs[g4]); }
;           float run = carry;
; #pragma unroll
;     ...
;             const float b3 = run + (h == 0 ? pc[g4] : 0.f);
;             const float b2 = b3 + lo[4 * g4 + 3];
;             const float b1 = b2 + lo[4 * g4 + 2];
;             const float b0 = b1 + lo[4 * g4 + 1];
;             st[kb][4 * g4 + 3] = fexp(st[kb][4 * g4 + 3] + lo[4 * g4 + 3] + b3);
;             st[kb][4 * g4 + 2] = fexp(st[kb][4 * g4 + 2] + lo[4 * g4 + 2] + b2);
;             st[kb][4 * g4 + 1] = fexp(st[kb][4 * g4 + 1] + lo[4 * g4 + 1] + b1);
;             st[kb][4 * g4 + 0] = fexp(st[kb][4 * g4 + 0] + lo[4 * g4 + 0] + b0);
;             run += cs[g4] + pc[g4];
;           }
;           carry = run;
	v_log_f32_e32 v3, v3
	v_mul_f32_e64 v7, |v77|, s29
	s_or_b64 s[8:9], vcc, s[8:9]
	v_exp_f32_e32 v7, v7
	v_cndmask_b32_e64 v71, 0, -v5, s[8:9]
	v_max_f32_e32 v5, v76, v76
	v_max_f32_e32 v5, 0, v5
	v_fmac_f32_e32 v5, 0x3f317218, v3
	v_add_u32_e32 v3, -7, v0
	v_cndmask_b32_e64 v68, v112, v75, s[8:9]
	v_cmp_lt_i32_e64 s[8:9], v3, v98
	v_add_f32_e32 v3, 1.0, v7
	v_log_f32_e32 v3, v3
	v_mul_f32_e64 v7, |v78|, s29
	s_or_b64 s[8:9], vcc, s[8:9]
	v_exp_f32_e32 v7, v7
	v_cndmask_b32_e64 v69, 0, -v5, s[8:9]
	v_max_f32_e32 v5, v77, v77
	v_max_f32_e32 v5, 0, v5
	v_fmac_f32_e32 v5, 0x3f317218, v3
	v_add_u32_e32 v3, -6, v0
	v_cndmask_b32_e64 v70, v112, v76, s[8:9]
	v_cmp_lt_i32_e64 s[8:9], v3, v98
	v_add_f32_e32 v3, 1.0, v7
	v_log_f32_e32 v3, v3
	v_mul_f32_e64 v7, |v79|, s29
	s_or_b64 s[8:9], vcc, s[8:9]
	v_exp_f32_e32 v7, v7
	v_cndmask_b32_e64 v72, 0, -v5, s[8:9]
	v_max_f32_e32 v5, v78, v78
	v_max_f32_e32 v5, 0, v5
	v_fmac_f32_e32 v5, 0x3f317218, v3
	v_add_u32_e32 v3, -5, v0
	v_cndmask_b32_e64 v73, v112, v77, s[8:9]
	v_cmp_lt_i32_e64 s[8:9], v3, v98
	v_add_f32_e32 v3, 1.0, v7
	v_log_f32_e32 v3, v3
	s_or_b64 s[8:9], vcc, s[8:9]
	v_cndmask_b32_e64 v74, 0, -v5, s[8:9]
	v_max_f32_e32 v5, v79, v79
	v_max_f32_e32 v5, 0, v5
	v_fmac_f32_e32 v5, 0x3f317218, v3
	v_add_u32_e32 v3, -4, v0
	v_cndmask_b32_e64 v75, v112, v78, s[8:9]
	v_cmp_lt_i32_e64 s[8:9], v3, v98
	s_or_b64 s[8:9], vcc, s[8:9]
	v_add_f32_e32 v3, v4, v11
	v_cndmask_b32_e64 v76, 0, -v5, s[8:9]
	v_add_f32_e32 v5, v15, v66
	v_add_f32_e32 v3, v3, v5
	v_mov_b32_e32 v5, v3
	v_mov_b32_e32 v7, v3
	s_nop 1
	v_permlane32_swap_b32_e32 v5, v7
	v_cndmask_b32_e64 v77, v112, v79, s[8:9]
	v_cmp_eq_u32_e64 s[8:9], v5, v3
	v_add_f32_e32 v9, v134, v136
	v_add_f32_e32 v140, v13, v6
	v_cndmask_b32_e64 v5, v5, v7, s[8:9]
	v_add_f32_e32 v7, v130, v132
	v_add_f32_e32 v78, v7, v9
	v_mov_b32_e32 v7, v78
	v_mov_b32_e32 v9, v78
	s_nop 1
	v_permlane32_swap_b32_e32 v7, v9
	v_cmp_eq_u32_e64 s[8:9], v7, v78
	v_add_f32_e32 v12, v65, v71
	v_add_f32_e32 v77, v77, v76
	v_cndmask_b32_e64 v79, v7, v9, s[8:9]
	v_add_f32_e32 v7, v69, v72
	v_add_f32_e32 v9, v74, v76
	v_pk_add_f32 v[6:7], v[6:7], v[8:9]
	v_add_f32_e32 v75, v75, v74
	v_mov_b32_e32 v9, v7
	v_mov_b32_e32 v13, v7
	s_nop 1
	v_permlane32_swap_b32_e32 v9, v13
	v_cmp_eq_u32_e64 s[8:9], v9, v7
	v_add_f32_e32 v73, v73, v72
	v_add_f32_e32 v139, v67, v65
	v_cndmask_b32_e64 v13, v9, v13, s[8:9]
	v_pk_add_f32 v[6:7], v[6:7], v[12:13]
	v_add_f32_e32 v138, v68, v71
	v_mov_b32_e32 v9, v6
	v_mov_b32_e32 v12, v6
	s_nop 1
	v_permlane32_swap_b32_e32 v9, v12
	v_cmp_eq_u32_e64 s[8:9], v9, v6
	v_add_f32_e32 v70, v70, v69
	v_add_f32_e32 v64, v64, v8
	v_cndmask_b32_e64 v108, v9, v12, s[8:9]
	v_cndmask_b32_e64 v9, 0, v13, s[6:7]
	v_add_f32_e32 v9, v109, v9
	v_add_f32_e32 v12, v76, v9
	v_add_f32_e32 v9, v77, v9
	v_mul_f32_e32 v9, 0x3fb8aa3b, v9
	v_add_f32_e32 v13, v74, v12
	v_exp_f32_e32 v67, v9
	v_add_f32_e32 v9, v75, v12
	v_mul_f32_e32 v68, 0x3fb8aa3b, v9
	v_add_f32_e32 v9, v73, v13
	v_add_f32_e32 v72, v72, v13
	v_mul_f32_e32 v9, 0x3fb8aa3b, v9
	v_exp_f32_e32 v69, v9
	v_add_f32_e32 v9, v70, v72
	v_mul_f32_e32 v70, 0x3fb8aa3b, v9
	v_cndmask_b32_e64 v9, 0, v108, s[6:7]
	v_pk_add_f32 v[6:7], v[6:7], v[108:109]
	v_add_f32_e32 v108, v128, v15
	v_add_f32_e32 v9, v9, v7
	v_add_f32_e32 v12, v71, v9
	v_add_f32_e32 v9, v138, v9
	v_mul_f32_e32 v9, 0x3fb8aa3b, v9
	v_add_f32_e32 v13, v65, v12
	v_exp_f32_e32 v71, v9
	v_add_f32_e32 v9, v139, v12
	v_mul_f32_e32 v72, 0x3fb8aa3b, v9
	v_add_f32_e32 v9, v64, v13
	v_pk_add_f32 v[64:65], v[6:7], v[6:7] op_sel:[0,1] op_sel_hi:[1,0]
	v_cndmask_b32_e64 v6, 0, v79, s[6:7]
	v_add_f32_e32 v6, v6, v64
	v_add_f32_e32 v12, v137, v136
	v_add_f32_e32 v7, v136, v6
	v_add_f32_e32 v6, v12, v6
	v_mul_f32_e32 v6, 0x3fb8aa3b, v6
	v_add_f32_e32 v8, v8, v13
	v_exp_f32_e32 v65, v6
	v_add_f32_e32 v6, v135, v134
	v_add_f32_e32 v8, v140, v8
	v_add_f32_e32 v6, v6, v7
	v_mul_f32_e32 v8, 0x3fb8aa3b, v8
	v_mul_f32_e32 v6, 0x3fb8aa3b, v6
	v_exp_f32_e32 v74, v8
	v_add_f32_e32 v8, v134, v7
	v_exp_f32_e32 v75, v6
	v_add_f32_e32 v6, v133, v132
	v_add_f32_e32 v6, v6, v8
	v_mul_f32_e32 v9, 0x3fb8aa3b, v9
	v_mul_f32_e32 v6, 0x3fb8aa3b, v6
	v_exp_f32_e32 v73, v9
	v_add_f32_e32 v9, v132, v8
	v_exp_f32_e32 v76, v6
	v_add_f32_e32 v6, v131, v130
	v_add_f32_e32 v6, v6, v9
	v_mul_f32_e32 v6, 0x3fb8aa3b, v6
	v_exp_f32_e32 v77, v6
	v_mul_f32_e64 v6, |v48|, s29
	v_exp_f32_e32 v6, v6
	v_add_f32_e32 v128, v10, v4
	v_max_f32_e32 v4, v48, v48
	v_max_f32_e32 v4, 0, v4
	v_add_f32_e32 v6, 1.0, v6
	v_log_f32_e32 v6, v6
	v_cmp_lt_i32_e64 s[8:9], v2, v98
	s_or_b64 s[8:9], vcc, s[8:9]
	v_add_f32_e32 v13, v78, v79
	v_fmac_f32_e32 v4, 0x3f317218, v6
	v_mul_f32_e64 v6, |v49|, s29
	v_exp_f32_e32 v7, v6
	v_cndmask_b32_e64 v6, 0, -v4, s[8:9]
	v_max_f32_e32 v4, v49, v49
	v_max_f32_e32 v4, 0, v4
	v_add_f32_e32 v2, 1.0, v7
	v_log_f32_e32 v2, v2
	v_mul_f32_e64 v7, |v50|, s29
	v_exp_f32_e32 v7, v7
	v_add_f32_e32 v79, v129, v66
	v_fmac_f32_e32 v4, 0x3f317218, v2
	v_subrev_u32_e32 v2, 62, v0
	v_cndmask_b32_e64 v129, v112, v48, s[8:9]
	v_cmp_lt_i32_e64 s[8:9], v2, v98
	v_add_f32_e32 v2, 1.0, v7
	v_log_f32_e32 v2, v2
	v_mul_f32_e64 v7, |v51|, s29
	s_or_b64 s[8:9], vcc, s[8:9]
	v_exp_f32_e32 v7, v7
	v_cndmask_b32_e64 v8, 0, -v4, s[8:9]
	v_max_f32_e32 v4, v50, v50
	v_max_f32_e32 v4, 0, v4
	v_fmac_f32_e32 v4, 0x3f317218, v2
	v_subrev_u32_e32 v2, 61, v0
	v_cndmask_b32_e64 v130, v112, v49, s[8:9]
	v_cmp_lt_i32_e64 s[8:9], v2, v98
	v_add_f32_e32 v2, 1.0, v7
	v_log_f32_e32 v2, v2
	v_mul_f32_e64 v7, |v52|, s29
	s_or_b64 s[8:9], vcc, s[8:9]
	v_exp_f32_e32 v7, v7
	v_cndmask_b32_e64 v10, 0, -v4, s[8:9]
	v_max_f32_e32 v4, v51, v51
	v_max_f32_e32 v4, 0, v4
; DI float fexp(float x) { return __builtin_amdgcn_exp2f(x * LOG2E); }
; DI float flog(float x) { return __builtin_amdgcn_logf(x) * 0.6931471805599453f; }
; DI void stick_attn_phase(const Params& p, char* smem) {
;     ...
;           float lo[16], cs[4], pc[4];
; #pragma unroll
;           for (int i = 0; i < 16; ++i) {
;             const float z = st[kb][i];
;             const float sp = fmaxf(z, 0.f) + flog(1.f + fexp(-fabsf(z)));
;             bool valid = true;
;             if (need_mask) valid = (k0 + kb * 32 + (i & 3) + 8 * (i >> 2) + 4 * h) < tq;
;             lo[i] = valid ? -sp : 0.f;
;             st[kb][i] = valid ? z : -INFINITY;
;           }
; #pragma unroll
;           for (int g4 = 0; g4 < 4; ++g4) { cs[g4] = (lo[4 * g4] + lo[4 * g4 + 1]) + (lo[4 * g4 + 2] + lo[4 * g4 + 3]); pc[g4] = xhalf(cs[g4]); }
	v_fmac_f32_e32 v4, 0x3f317218, v2
	v_subrev_u32_e32 v2, 60, v0
	v_cndmask_b32_e64 v131, v112, v50, s[8:9]
	v_cmp_lt_i32_e64 s[8:9], v2, v98
	v_add_f32_e32 v2, 1.0, v7
	v_log_f32_e32 v2, v2
	v_mul_f32_e64 v7, |v53|, s29
	s_or_b64 s[8:9], vcc, s[8:9]
	v_exp_f32_e32 v7, v7
	v_add_f32_e32 v109, v14, v11
	v_cndmask_b32_e64 v14, 0, -v4, s[8:9]
	v_max_f32_e32 v4, v52, v52
	v_max_f32_e32 v4, 0, v4
	v_fmac_f32_e32 v4, 0x3f317218, v2
	v_subrev_u32_e32 v2, 55, v0
	v_cndmask_b32_e64 v132, v112, v51, s[8:9]
	v_cmp_lt_i32_e64 s[8:9], v2, v98
	v_add_f32_e32 v2, 1.0, v7
	v_log_f32_e32 v2, v2
	v_mul_f32_e64 v7, |v54|, s29
	s_or_b64 s[8:9], vcc, s[8:9]
	v_exp_f32_e32 v7, v7
	v_cndmask_b32_e64 v133, 0, -v4, s[8:9]
	v_max_f32_e32 v4, v53, v53
	v_max_f32_e32 v4, 0, v4
	v_fmac_f32_e32 v4, 0x3f317218, v2
	v_subrev_u32_e32 v2, 54, v0
	v_cndmask_b32_e64 v134, v112, v52, s[8:9]
	v_cmp_lt_i32_e64 s[8:9], v2, v98
	v_add_f32_e32 v2, 1.0, v7
	v_log_f32_e32 v2, v2
	v_mul_f32_e64 v7, |v55|, s29
	s_or_b64 s[8:9], vcc, s[8:9]
	v_exp_f32_e32 v7, v7
	v_cndmask_b32_e64 v135, 0, -v4, s[8:9]
	v_max_f32_e32 v4, v54, v54
	v_max_f32_e32 v4, 0, v4
	v_fmac_f32_e32 v4, 0x3f317218, v2
	v_subrev_u32_e32 v2, 53, v0
	v_cndmask_b32_e64 v136, v112, v53, s[8:9]
	v_cmp_lt_i32_e64 s[8:9], v2, v98
	v_add_f32_e32 v2, 1.0, v7
	v_log_f32_e32 v2, v2
	v_mul_f32_e64 v7, |v56|, s29
	s_or_b64 s[8:9], vcc, s[8:9]
	v_exp_f32_e32 v7, v7
	v_cndmask_b32_e64 v137, 0, -v4, s[8:9]
	v_max_f32_e32 v4, v55, v55
	v_max_f32_e32 v4, 0, v4
	v_fmac_f32_e32 v4, 0x3f317218, v2
	v_subrev_u32_e32 v2, 52, v0
	v_cndmask_b32_e64 v54, v112, v54, s[8:9]
	v_cmp_lt_i32_e64 s[8:9], v2, v98
	v_add_f32_e32 v2, 1.0, v7
	v_log_f32_e32 v2, v2
	v_mul_f32_e64 v7, |v57|, s29
	s_or_b64 s[8:9], vcc, s[8:9]
	v_exp_f32_e32 v7, v7
	v_cndmask_b32_e64 v138, 0, -v4, s[8:9]
	v_max_f32_e32 v4, v56, v56
	v_max_f32_e32 v4, 0, v4
	v_fmac_f32_e32 v4, 0x3f317218, v2
	v_subrev_u32_e32 v2, 47, v0
	v_cndmask_b32_e64 v55, v112, v55, s[8:9]
	v_cmp_lt_i32_e64 s[8:9], v2, v98
	v_add_f32_e32 v2, 1.0, v7
	v_log_f32_e32 v2, v2
	v_mul_f32_e64 v7, |v58|, s29
	s_or_b64 s[8:9], vcc, s[8:9]
	v_exp_f32_e32 v7, v7
	v_cndmask_b32_e64 v139, 0, -v4, s[8:9]
	v_max_f32_e32 v4, v57, v57
	v_max_f32_e32 v4, 0, v4
	v_fmac_f32_e32 v4, 0x3f317218, v2
	v_subrev_u32_e32 v2, 46, v0
	v_cndmask_b32_e64 v56, v112, v56, s[8:9]
	v_cmp_lt_i32_e64 s[8:9], v2, v98
	v_add_f32_e32 v2, 1.0, v7
	v_log_f32_e32 v2, v2
	v_mul_f32_e64 v7, |v59|, s29
	s_or_b64 s[8:9], vcc, s[8:9]
	v_exp_f32_e32 v7, v7
	v_cndmask_b32_e64 v140, 0, -v4, s[8:9]
	v_max_f32_e32 v4, v58, v58
	v_max_f32_e32 v4, 0, v4
	v_fmac_f32_e32 v4, 0x3f317218, v2
	v_subrev_u32_e32 v2, 45, v0
	v_cndmask_b32_e64 v57, v112, v57, s[8:9]
	v_cmp_lt_i32_e64 s[8:9], v2, v98
	v_add_f32_e32 v2, 1.0, v7
	v_log_f32_e32 v2, v2
	v_mul_f32_e64 v7, |v60|, s29
	s_or_b64 s[8:9], vcc, s[8:9]
	v_exp_f32_e32 v7, v7
	v_cndmask_b32_e64 v141, 0, -v4, s[8:9]
	v_max_f32_e32 v4, v59, v59
	v_max_f32_e32 v4, 0, v4
	v_fmac_f32_e32 v4, 0x3f317218, v2
	v_subrev_u32_e32 v2, 44, v0
	v_cndmask_b32_e64 v58, v112, v58, s[8:9]
	v_cmp_lt_i32_e64 s[8:9], v2, v98
	v_add_f32_e32 v2, 1.0, v7
	v_log_f32_e32 v2, v2
	s_or_b64 s[8:9], vcc, s[8:9]
	v_cndmask_b32_e64 v142, 0, -v4, s[8:9]
	v_max_f32_e32 v4, v60, v60
	v_mul_f32_e64 v7, |v61|, s29
	v_max_f32_e32 v4, 0, v4
	v_exp_f32_e32 v7, v7
	v_fmac_f32_e32 v4, 0x3f317218, v2
	v_subrev_u32_e32 v2, 39, v0
	v_cndmask_b32_e64 v59, v112, v59, s[8:9]
	v_cmp_lt_i32_e64 s[8:9], v2, v98
	s_or_b64 s[8:9], vcc, s[8:9]
	v_mul_f32_e64 v9, |v62|, s29
	v_cndmask_b32_e64 v2, 0, -v4, s[8:9]
	v_add_f32_e32 v4, 1.0, v7
	v_log_f32_e32 v4, v4
	v_max_f32_e32 v7, v61, v61
	v_max_f32_e32 v7, 0, v7
	v_exp_f32_e32 v9, v9
	v_fmac_f32_e32 v7, 0x3f317218, v4
	v_subrev_u32_e32 v4, 38, v0
	v_cndmask_b32_e64 v60, v112, v60, s[8:9]
	v_cmp_lt_i32_e64 s[8:9], v4, v98
	s_or_b64 s[8:9], vcc, s[8:9]
	v_mul_f32_e64 v12, |v63|, s29
	v_cndmask_b32_e64 v4, 0, -v7, s[8:9]
	v_add_f32_e32 v7, 1.0, v9
	v_log_f32_e32 v7, v7
	v_exp_f32_e32 v48, v12
	v_max_f32_e32 v9, v62, v62
	v_max_f32_e32 v9, 0, v9
	v_fmac_f32_e32 v9, 0x3f317218, v7
	v_subrev_u32_e32 v7, 37, v0
	v_cndmask_b32_e64 v61, v112, v61, s[8:9]
	v_cmp_lt_i32_e64 s[8:9], v7, v98
	v_add_f32_e32 v7, 1.0, v48
	v_log_f32_e32 v7, v7
	s_or_b64 s[8:9], vcc, s[8:9]
	v_cndmask_b32_e64 v12, 0, -v9, s[8:9]
	v_max_f32_e32 v9, v63, v63
	v_subrev_u32_e32 v0, 36, v0
	v_cndmask_b32_e64 v62, v112, v62, s[8:9]
	v_max_f32_e32 v9, 0, v9
	v_cmp_lt_i32_e64 s[8:9], v0, v98
	v_fmac_f32_e32 v9, 0x3f317218, v7
	s_or_b64 vcc, vcc, s[8:9]
	v_cndmask_b32_e64 v48, 0, -v9, vcc
	v_add_f32_e32 v7, v133, v135
	v_add_f32_e32 v9, v137, v138
	v_add_f32_e32 v7, v7, v9
	v_mov_b32_e32 v9, v7
	v_mov_b32_e32 v49, v7
	s_nop 1
	v_permlane32_swap_b32_e32 v9, v49
	v_cndmask_b32_e32 v0, v112, v63, vcc
	v_cmp_eq_u32_e32 vcc, v9, v7
	v_add_f32_e32 v50, v141, v142
	v_cndmask_b32_e64 v78, 0, v5, s[6:7]
	v_cndmask_b32_e32 v9, v9, v49, vcc
	v_add_f32_e32 v49, v139, v140
	v_add_f32_e32 v63, v49, v50
	v_mov_b32_e32 v49, v63
	v_mov_b32_e32 v50, v63
	s_nop 1
	v_permlane32_swap_b32_e32 v49, v50
	v_cmp_eq_u32_e32 vcc, v49, v63
	v_pk_add_f32 v[52:53], v[2:3], v[4:5]
	v_add_f32_e32 v2, v60, v2
	v_cndmask_b32_e32 v143, v49, v50, vcc
	v_mov_b32_e32 v49, v64
	v_pk_add_f32 v[50:51], v[12:13], v[48:49]
	v_add_f32_e32 v0, v0, v48
	v_add_f32_e32 v13, v78, v51
	v_pk_add_f32 v[50:51], v[52:53], v[50:51]
	v_add_f32_e32 v49, v66, v13
	v_mov_b32_e32 v3, v50
	v_mov_b32_e32 v5, v50
	s_nop 1
	v_permlane32_swap_b32_e32 v3, v5
; #define MFMA(a, b, c) __builtin_amdgcn_mfma_f32_32x32x16_bf16((a), (b), (c), 0, 0, 0)
; template <int DV, int STEP>
; DI void pv_step(f32x16 (&ot)[DV / 32], const bf16x8 (&pk)[2][2], s16x4 (&fa)[DV / 32][2], s16x4 (&fb)[DV / 32][2], const unsigned (&a)[DV / 32]) {
;   constexpr int VP = 2 * DV, NDC = DV / 32;
;   tr_wait(fa);
;   if (STEP < 3) TrIssue<NDC, (((STEP + 1) >> 1) * 32 + ((STEP + 1) & 1) * 16) * VP, (((STEP + 1) >> 1) * 32 + ((STEP + 1) & 1) * 16 + 8) * VP>::run(fb, a);
; #pragma unroll
;   for (int dc = 0; dc < NDC; ++dc) {
;     const bf16x8 vf = __builtin_shufflevector(fa[dc][0], fa[dc][1], 0, 1, 2, 3, 4, 5, 6, 7);
;     ot[dc] = MFMA(vf, pk[STEP >> 1][STEP & 1], ot[dc]);
;   }
; }
; template <int DV>
; DI void pv_tile(f32x16 (&ot)[DV / 32], const bf16x8 (&pk)[2][2], char* sb, int lane) {
;   constexpr int VP = 2 * DV, NDC = DV / 32;
;   const int h = lane >> 5, i16 = lane & 15, qq = i16 >> 2, pp = i16 & 3, blk = (lane >> 4) & 1;
;   const int qx = (DV == 128) ? qq : (qq >> 1);
;   const unsigned vb = (unsigned)(size_t)(sb + 8192) + (4 * h + qq) * VP + 32 * blk + 8 * pp;
;   unsigned a[NDC];
; #pragma unroll
;   for (int dc = 0; dc < NDC; ++dc) a[dc] = vb + ((dc ^ qx) << 6);
;   s16x4 f0[NDC][2], f1[NDC][2];
;   TrIssue<NDC, 0, 8 * VP>::run(f0, a);
;   pv_step<DV, 0>(ot, pk, f0, f1, a);
;   pv_step<DV, 1>(ot, pk, f1, f0, a);
;   pv_step<DV, 2>(ot, pk, f0, f1, a);
;   pv_step<DV, 3>(ot, pk, f1, f0, a);
; }
; DI void stick_attn_phase(const Params& p, char* smem) {
;     ...
;           float run = carry;
; #pragma unroll
;     ...
;             const float b3 = run + (h == 0 ? pc[g4] : 0.f);
;             const float b2 = b3 + lo[4 * g4 + 3];
;             const float b1 = b2 + lo[4 * g4 + 2];
;             const float b0 = b1 + lo[4 * g4 + 1];
;             st[kb][4 * g4 + 3] = fexp(st[kb][4 * g4 + 3] + lo[4 * g4 + 3] + b3);
;             st[kb][4 * g4 + 2] = fexp(st[kb][4 * g4 + 2] + lo[4 * g4 + 2] + b2);
;             st[kb][4 * g4 + 1] = fexp(st[kb][4 * g4 + 1] + lo[4 * g4 + 1] + b1);
;             st[kb][4 * g4 + 0] = fexp(st[kb][4 * g4 + 0] + lo[4 * g4 + 0] + b0);
;             run += cs[g4] + pc[g4];
;           }
;           carry = run;
;           pk[kb][0] = pack8(st[kb], 0);
;           pk[kb][1] = pack8(st[kb], 1);
;         }
;         pv_tile<64>(ot, pk, sb, lane);
;         done = __all(carry < -105.f) ? 1u : 0u;
	v_add_f32_e32 v13, v79, v13
	v_cmp_eq_u32_e32 vcc, v3, v50
	v_mul_f32_e32 v13, 0x3fb8aa3b, v13
	v_add_f32_e32 v15, v15, v49
	v_cndmask_b32_e32 v3, v3, v5, vcc
	v_exp_f32_e32 v64, v13
	v_add_f32_e32 v13, v108, v49
	v_cndmask_b32_e64 v5, 0, v3, s[6:7]
	v_add_f32_e32 v11, v11, v15
	v_mul_f32_e32 v66, 0x3fb8aa3b, v13
	v_add_f32_e32 v13, v109, v15
	v_add_f32_e32 v5, v5, v51
	v_mul_f32_e32 v13, 0x3fb8aa3b, v13
	v_add_f32_e32 v79, v128, v11
	v_add_f32_e32 v11, v48, v5
	v_exp_f32_e32 v78, v13
	v_add_f32_e32 v13, v12, v11
	v_add_f32_e32 v15, v4, v13
	v_add_f32_e32 v2, v2, v15
	v_mul_f32_e32 v60, 0x3fb8aa3b, v2
	v_add_f32_e32 v2, v50, v3
	v_add_f32_e32 v0, v0, v5
	v_add_f32_e32 v5, v62, v12
	v_add_f32_e32 v15, v2, v51
	v_cndmask_b32_e64 v2, 0, v143, s[6:7]
	v_add_f32_e32 v5, v5, v11
	v_add_f32_e32 v2, v2, v15
	v_add_f32_e32 v11, v59, v142
	v_add_f32_e32 v3, v142, v2
	v_add_f32_e32 v2, v11, v2
	v_add_f32_e32 v4, v61, v4
	v_mul_f32_e32 v2, 0x3fb8aa3b, v2
	v_add_f32_e32 v4, v4, v13
	v_exp_f32_e32 v50, v2
	v_add_f32_e32 v2, v58, v141
	v_mul_f32_e32 v4, 0x3fb8aa3b, v4
	v_add_f32_e32 v2, v2, v3
	v_exp_f32_e32 v53, v4
	v_add_f32_e32 v4, v141, v3
	v_mul_f32_e32 v51, 0x3fb8aa3b, v2
	v_add_f32_e32 v2, v57, v140
	v_add_f32_e32 v2, v2, v4
	v_mul_f32_e32 v2, 0x3fb8aa3b, v2
	v_mul_f32_e32 v52, 0x3fb8aa3b, v5
	v_add_f32_e32 v5, v140, v4
	v_exp_f32_e32 v57, v2
	v_add_f32_e32 v2, v56, v139
	v_add_f32_e32 v2, v2, v5
	v_mul_f32_e32 v2, 0x3fb8aa3b, v2
	v_add_f32_e32 v11, v63, v143
	v_exp_f32_e32 v56, v2
	v_pk_add_f32 v[2:3], v[10:11], v[14:15]
	v_pk_add_f32 v[4:5], v[6:7], v[8:9]
	v_cndmask_b32_e64 v12, 0, v9, s[6:7]
	v_pk_add_f32 v[48:49], v[4:5], v[2:3]
	v_add_f32_e32 v13, v55, v138
	v_mov_b32_e32 v2, v48
	v_mov_b32_e32 v4, v48
	s_nop 1
	v_permlane32_swap_b32_e32 v2, v4
	v_cmp_eq_u32_e32 vcc, v2, v48
	v_add_f32_e32 v54, v54, v137
	v_add_f32_e32 v55, v136, v135
	v_cndmask_b32_e32 v15, v2, v4, vcc
	v_add_f32_e32 v2, v12, v3
	v_add_f32_e32 v3, v138, v2
	v_add_f32_e32 v2, v13, v2
	v_add_f32_e32 v4, v137, v3
	v_mul_f32_e32 v2, 0x3fb8aa3b, v2
	v_exp_f32_e32 v7, v2
	v_add_f32_e32 v2, v54, v3
	v_add_f32_e32 v3, v55, v4
	v_add_f32_e32 v58, v134, v133
	v_add_f32_e32 v5, v135, v4
	v_mul_f32_e32 v3, 0x3fb8aa3b, v3
	v_exp_f32_e32 v4, v3
	v_add_f32_e32 v3, v58, v5
	v_cndmask_b32_e64 v5, 0, v15, s[6:7]
	v_add_f32_e32 v5, v5, v49
	v_add_f32_e32 v9, v14, v5
	v_add_f32_e32 v11, v10, v9
	v_add_f32_e32 v12, v8, v11
	v_add_f32_e32 v8, v130, v8
	v_add_f32_e32 v6, v129, v6
	v_add_f32_e32 v13, v132, v14
	v_add_f32_e32 v10, v131, v10
	v_add_f32_e32 v8, v8, v11
	v_add_f32_e32 v6, v6, v12
	v_add_f32_e32 v5, v13, v5
	v_add_f32_e32 v9, v10, v9
	v_mul_f32_e32 v8, 0x3fb8aa3b, v8
	v_mul_f32_e32 v6, 0x3fb8aa3b, v6
	v_mul_f32_e32 v2, 0x3fb8aa3b, v2
	v_mul_f32_e32 v3, 0x3fb8aa3b, v3
	v_mul_f32_e32 v5, 0x3fb8aa3b, v5
	v_mul_f32_e32 v9, 0x3fb8aa3b, v9
	v_exp_f32_e32 v8, v8
	v_exp_f32_e32 v6, v6
	v_exp_f32_e32 v5, v5
	v_exp_f32_e32 v9, v9
	v_exp_f32_e32 v10, v3
	v_exp_f32_e32 v11, v2
	v_cvt_pk_bf16_f32 v2, v6, v8
	v_add_u32_e32 v6, s0, v117
	v_cvt_pk_bf16_f32 v3, v9, v5
	v_cvt_pk_bf16_f32 v4, v10, v4
	v_cvt_pk_bf16_f32 v5, v11, v7
	v_add_u32_e32 v14, v6, v118
	v_add_u32_e32 v54, v6, v119
	ds_read_b64_tr_b16 v[10:11], v14 offset:0
	ds_read_b64_tr_b16 v[12:13], v14 offset:0x400
	ds_read_b64_tr_b16 v[6:7], v54 offset:0
	ds_read_b64_tr_b16 v[8:9], v54 offset:0x400
	v_mul_f32_e32 v0, 0x3fb8aa3b, v0
	v_exp_f32_e32 v0, v0
	s_waitcnt lgkmcnt(2)
	v_mfma_f32_32x32x16_bf16 v[32:47], v[10:13], v[2:5], v[32:47]
	v_exp_f32_e32 v11, v51
	v_exp_f32_e32 v12, v60
	v_exp_f32_e32 v13, v52
	v_cvt_pk_bf16_f32 v10, v56, v57
	v_cvt_pk_bf16_f32 v11, v11, v50
	v_cvt_pk_bf16_f32 v12, v12, v53
	v_cvt_pk_bf16_f32 v13, v13, v0
	s_waitcnt lgkmcnt(0)
	v_mfma_f32_32x32x16_bf16 v[16:31], v[6:9], v[2:5], v[16:31]
	ds_read_b64_tr_b16 v[6:7], v14 offset:0x800
	ds_read_b64_tr_b16 v[8:9], v14 offset:0xc00
	ds_read_b64_tr_b16 v[2:3], v54 offset:0x800
	ds_read_b64_tr_b16 v[4:5], v54 offset:0xc00
	v_mul_f32_e32 v0, 0x3fb8aa3b, v79
	v_exp_f32_e32 v0, v0
	s_waitcnt lgkmcnt(2)
	v_mfma_f32_32x32x16_bf16 v[32:47], v[6:9], v[10:13], v[32:47]
	v_exp_f32_e32 v7, v66
	v_cvt_pk_bf16_f32 v8, v77, v76
	v_cvt_pk_bf16_f32 v9, v75, v65
	v_cvt_pk_bf16_f32 v6, v0, v78
	v_cvt_pk_bf16_f32 v7, v7, v64
	v_exp_f32_e32 v0, v72
	s_waitcnt lgkmcnt(0)
	v_mfma_f32_32x32x16_bf16 v[16:31], v[2:5], v[10:13], v[16:31]
	ds_read_b64_tr_b16 v[10:11], v14 offset:0x1000
	ds_read_b64_tr_b16 v[12:13], v14 offset:0x1400
	ds_read_b64_tr_b16 v[2:3], v54 offset:0x1000
	ds_read_b64_tr_b16 v[4:5], v54 offset:0x1400
	s_nop 0
	s_nop 0
	s_waitcnt lgkmcnt(2)
	v_mfma_f32_32x32x16_bf16 v[32:47], v[10:13], v[6:9], v[32:47]
	v_exp_f32_e32 v12, v70
	v_exp_f32_e32 v13, v68
	v_cvt_pk_bf16_f32 v10, v74, v73
	v_cvt_pk_bf16_f32 v11, v0, v71
	v_cvt_pk_bf16_f32 v12, v12, v69
	v_cvt_pk_bf16_f32 v13, v13, v67
	v_add_f32_e32 v0, v48, v15
	s_waitcnt lgkmcnt(0)
	v_mfma_f32_32x32x16_bf16 v[16:31], v[2:5], v[6:9], v[16:31]
	ds_read_b64_tr_b16 v[6:7], v14 offset:0x1800
	ds_read_b64_tr_b16 v[8:9], v14 offset:0x1c00
	ds_read_b64_tr_b16 v[2:3], v54 offset:0x1800
	ds_read_b64_tr_b16 v[4:5], v54 offset:0x1c00
	v_add_f32_e32 v109, v0, v49
	v_cmp_gt_f32_e32 vcc, s30, v109
	s_cmp_eq_u64 vcc, exec
	s_cselect_b64 s[0:1], -1, 0
	v_cndmask_b32_e64 v48, 0, 1, s[0:1]
	s_waitcnt lgkmcnt(2)
	v_mfma_f32_32x32x16_bf16 v[32:47], v[6:9], v[10:13], v[32:47]
	s_waitcnt lgkmcnt(0)
	v_mfma_f32_32x32x16_bf16 v[16:31], v[2:5], v[10:13], v[16:31]
	s_branch .LBB0_2606
